# GEMM main loops and their peeled first iterations: the per-MMA-block s_setprio 1/0 toggles removed (48 in the loops)
# speedup vs baseline: 1.0172x; 1.0014x over previous
.LBB0_490:
	v_mov_b64_e32 v[2:3], s[26:27]
	s_ashr_i32 s41, s40, 31
	v_cmp_lt_i64_e32 vcc, s[16:17], v[2:3]
	s_lshl_b64 s[16:17], s[40:41], 19
	s_add_u32 s44, s46, s16
	s_addc_u32 s45, s47, s17
	s_and_b64 s[16:17], vcc, exec
	s_cselect_b32 s9, s45, s13
	s_cselect_b32 s11, s44, s12
	s_ashr_i32 s39, s38, 31
	s_lshl_b64 s[16:17], s[38:39], 19
	s_add_u32 s54, s71, s16
	s_addc_u32 s55, s73, s17
	s_and_b64 s[16:17], vcc, exec
	s_cselect_b32 s39, s55, s15
	s_cselect_b32 s41, s54, s14
	s_add_u32 s12, s12, 0x40080
	s_addc_u32 s13, s13, 0
	s_add_u32 s62, s14, 0x100
	s_addc_u32 s63, s15, 0
	s_mov_b32 s64, -2
	s_add_u32 s14, s12, 0xfffc0080
	s_addc_u32 s15, s13, -1
	s_add_i32 s65, 0, 0x10000
	v_add_u32_e32 v0, s65, v230
	ds_read_b128 v[2:5], v0
	ds_read_b128 v[6:9], v0 offset:1024
	ds_read_b128 v[10:13], v0 offset:2048
	ds_read_b128 v[14:17], v0 offset:3072
	s_cmp_eq_u32 s64, 12
	s_cselect_b32 s17, s9, s15
	s_cselect_b32 s16, s11, s14
	s_cselect_b32 s15, s39, s63
	s_cselect_b32 s14, s41, s62
	v_lshl_add_u64 v[50:51], s[12:13], 0, v[214:215]
	s_add_i32 m0, s23, 0xc000
	ds_read_b128 v[18:21], v232
	ds_read_b128 v[22:25], v232 offset:1024
	ds_read_b128 v[26:29], v232 offset:2048
	ds_read_b128 v[30:33], v232 offset:3072
	ds_read_b128 v[34:37], v232 offset:4096
	ds_read_b128 v[38:41], v232 offset:5120
	ds_read_b128 v[42:45], v232 offset:6144
	ds_read_b128 v[46:49], v232 offset:7168
	global_load_lds_dwordx4 v[50:51], off
	v_lshl_add_u64 v[50:51], s[12:13], 0, v[216:217]
	s_add_i32 m0, s23, 0xe000
	s_nop 0
	global_load_lds_dwordx4 v[50:51], off
	s_waitcnt lgkmcnt(8)
	s_barrier
	s_waitcnt lgkmcnt(0)
	s_waitcnt lgkmcnt(0)
	v_mfma_f32_16x16x32_bf16 v[158:161], v[2:5], v[34:37], 0
	v_mfma_f32_16x16x32_bf16 v[154:157], v[10:13], v[34:37], 0
	v_mfma_f32_16x16x32_bf16 v[138:141], v[2:5], v[42:45], 0
	v_mfma_f32_16x16x32_bf16 v[134:137], v[10:13], v[42:45], 0
	v_mfma_f32_16x16x32_bf16 v[50:53], v[2:5], v[18:21], 0
	v_mfma_f32_16x16x32_bf16 v[54:57], v[10:13], v[18:21], 0
	v_mfma_f32_16x16x32_bf16 v[58:61], v[2:5], v[26:29], 0
	v_mfma_f32_16x16x32_bf16 v[150:153], v[10:13], v[26:29], 0
	v_mfma_f32_16x16x32_bf16 v[158:161], v[6:9], v[38:41], v[158:161]
	v_mfma_f32_16x16x32_bf16 v[154:157], v[14:17], v[38:41], v[154:157]
	v_mfma_f32_16x16x32_bf16 v[138:141], v[6:9], v[46:49], v[138:141]
	v_mfma_f32_16x16x32_bf16 v[134:137], v[14:17], v[46:49], v[134:137]
	v_mfma_f32_16x16x32_bf16 v[50:53], v[6:9], v[22:25], v[50:53]
	v_mfma_f32_16x16x32_bf16 v[54:57], v[14:17], v[22:25], v[54:57]
	v_mfma_f32_16x16x32_bf16 v[58:61], v[6:9], v[30:33], v[58:61]
	v_mfma_f32_16x16x32_bf16 v[150:153], v[14:17], v[30:33], v[150:153]
	s_barrier
	s_add_i32 s86, 0, 0x14000
	s_add_i32 s65, s65, s22
	v_add_u32_e32 v0, s86, v230
	v_lshl_add_u64 v[222:223], s[14:15], 0, v[208:209]
	s_mov_b32 m0, s65
	ds_read_b128 v[162:165], v0
	ds_read_b128 v[174:177], v0 offset:1024
	ds_read_b128 v[178:181], v0 offset:2048
	ds_read_b128 v[182:185], v0 offset:3072
	global_load_lds_dwordx4 v[222:223], off
	v_lshl_add_u64 v[226:227], s[14:15], 0, v[212:213]
	s_add_i32 m0, s65, 0x2000
	s_nop 0
	global_load_lds_dwordx4 v[226:227], off
	s_barrier
	s_waitcnt lgkmcnt(0)
	s_waitcnt lgkmcnt(0)
	v_mfma_f32_16x16x32_bf16 v[186:189], v[162:165], v[18:21], 0
	v_mfma_f32_16x16x32_bf16 v[18:21], v[178:181], v[18:21], 0
	v_mfma_f32_16x16x32_bf16 v[186:189], v[174:177], v[22:25], v[186:189]
	v_mfma_f32_16x16x32_bf16 v[18:21], v[182:185], v[22:25], v[18:21]
	v_mfma_f32_16x16x32_bf16 v[22:25], v[162:165], v[26:29], 0
	v_mfma_f32_16x16x32_bf16 v[26:29], v[178:181], v[26:29], 0
	v_mfma_f32_16x16x32_bf16 v[22:25], v[174:177], v[30:33], v[22:25]
	v_mfma_f32_16x16x32_bf16 v[26:29], v[182:185], v[30:33], v[26:29]
	v_mfma_f32_16x16x32_bf16 v[30:33], v[162:165], v[34:37], 0
	v_mfma_f32_16x16x32_bf16 v[34:37], v[178:181], v[34:37], 0
	v_mfma_f32_16x16x32_bf16 v[30:33], v[174:177], v[38:41], v[30:33]
	v_mfma_f32_16x16x32_bf16 v[34:37], v[182:185], v[38:41], v[34:37]
	v_mfma_f32_16x16x32_bf16 v[38:41], v[162:165], v[42:45], 0
	v_mfma_f32_16x16x32_bf16 v[42:45], v[178:181], v[42:45], 0
	v_mfma_f32_16x16x32_bf16 v[38:41], v[174:177], v[46:49], v[38:41]
	v_mfma_f32_16x16x32_bf16 v[42:45], v[182:185], v[46:49], v[42:45]
	s_mov_b32 m0, s23
	v_lshl_add_u64 v[238:239], s[16:17], 0, v[206:207]
	s_barrier
	ds_read_b128 v[46:49], v232 offset:16384
	ds_read_b128 v[126:129], v232 offset:17408
	ds_read_b128 v[130:133], v232 offset:18432
	ds_read_b128 v[142:145], v232 offset:19456
	ds_read_b128 v[146:149], v232 offset:20480
	ds_read_b128 v[166:169], v232 offset:21504
	ds_read_b128 v[170:173], v232 offset:22528
	ds_read_b128 v[190:193], v232 offset:23552
	global_load_lds_dwordx4 v[238:239], off
	v_lshl_add_u64 v[240:241], s[16:17], 0, v[210:211]
	s_mov_b32 m0, s72
	s_nop 0
	global_load_lds_dwordx4 v[240:241], off
	s_barrier
	s_waitcnt lgkmcnt(0)
	s_waitcnt lgkmcnt(0)
	v_mfma_f32_16x16x32_bf16 v[122:125], v[2:5], v[46:49], 0
	v_mfma_f32_16x16x32_bf16 v[118:121], v[10:13], v[46:49], 0
	v_mfma_f32_16x16x32_bf16 v[106:109], v[2:5], v[130:133], 0
	v_mfma_f32_16x16x32_bf16 v[102:105], v[10:13], v[130:133], 0
	v_mfma_f32_16x16x32_bf16 v[90:93], v[2:5], v[146:149], 0
	v_mfma_f32_16x16x32_bf16 v[86:89], v[10:13], v[146:149], 0
	v_mfma_f32_16x16x32_bf16 v[2:5], v[2:5], v[170:173], 0
	v_mfma_f32_16x16x32_bf16 v[122:125], v[6:9], v[126:129], v[122:125]
	v_mfma_f32_16x16x32_bf16 v[118:121], v[14:17], v[126:129], v[118:121]
	v_mfma_f32_16x16x32_bf16 v[106:109], v[6:9], v[142:145], v[106:109]
	v_mfma_f32_16x16x32_bf16 v[102:105], v[14:17], v[142:145], v[102:105]
	v_mfma_f32_16x16x32_bf16 v[90:93], v[6:9], v[166:169], v[90:93]
	v_mfma_f32_16x16x32_bf16 v[86:89], v[14:17], v[166:169], v[86:89]
	v_mfma_f32_16x16x32_bf16 v[2:5], v[6:9], v[190:193], v[2:5]
	v_mfma_f32_16x16x32_bf16 v[6:9], v[10:13], v[170:173], 0
	v_mfma_f32_16x16x32_bf16 v[6:9], v[14:17], v[190:193], v[6:9]
	s_barrier
	s_add_u32 s66, s14, 0x40000
	s_addc_u32 s67, s15, 0
	s_add_i32 s65, s86, s22
	v_lshl_add_u64 v[10:11], s[66:67], 0, v[208:209]
	s_mov_b32 m0, s65
	s_nop 0
	global_load_lds_dwordx4 v[10:11], off
	v_lshl_add_u64 v[10:11], s[66:67], 0, v[212:213]
	s_add_i32 m0, s65, 0x2000
	s_nop 0
	global_load_lds_dwordx4 v[10:11], off
	s_waitcnt vmcnt(6)
	s_barrier
	v_mfma_f32_16x16x32_bf16 v[70:73], v[178:181], v[130:133], 0
	v_mfma_f32_16x16x32_bf16 v[94:97], v[182:185], v[142:145], v[70:73]
	v_mfma_f32_16x16x32_bf16 v[70:73], v[162:165], v[146:149], 0
	v_mfma_f32_16x16x32_bf16 v[82:85], v[174:177], v[166:169], v[70:73]
	v_mfma_f32_16x16x32_bf16 v[70:73], v[178:181], v[146:149], 0
	v_mfma_f32_16x16x32_bf16 v[66:69], v[162:165], v[170:173], 0
	v_mfma_f32_16x16x32_bf16 v[62:65], v[178:181], v[170:173], 0
	v_mfma_f32_16x16x32_bf16 v[10:13], v[162:165], v[46:49], 0
	v_mfma_f32_16x16x32_bf16 v[14:17], v[178:181], v[46:49], 0
	v_mfma_f32_16x16x32_bf16 v[46:49], v[162:165], v[130:133], 0
	v_mfma_f32_16x16x32_bf16 v[78:81], v[182:185], v[166:169], v[70:73]
	v_mfma_f32_16x16x32_bf16 v[66:69], v[174:177], v[190:193], v[66:69]
	v_mfma_f32_16x16x32_bf16 v[62:65], v[182:185], v[190:193], v[62:65]
	v_mfma_f32_16x16x32_bf16 v[10:13], v[174:177], v[126:129], v[10:13]
	v_mfma_f32_16x16x32_bf16 v[14:17], v[182:185], v[126:129], v[14:17]
	v_mfma_f32_16x16x32_bf16 v[46:49], v[174:177], v[142:145], v[46:49]
	s_add_i32 s65, 0, 0x18000
	v_add_u32_e32 v0, s65, v230
	s_barrier
	ds_read_b128 v[70:73], v0
	ds_read_b128 v[74:77], v0 offset:1024
	ds_read_b128 v[98:101], v0 offset:2048
	ds_read_b128 v[110:113], v0 offset:3072
	s_add_u32 s16, s16, 0x40000
	s_addc_u32 s17, s17, 0
	s_mov_b32 m0, s83
	v_lshl_add_u64 v[146:147], s[16:17], 0, v[206:207]
	ds_read_b128 v[114:117], v232 offset:32768
	ds_read_b128 v[126:129], v232 offset:33792
	ds_read_b128 v[130:133], v232 offset:34816
	ds_read_b128 v[142:145], v232 offset:35840
	ds_read_b128 v[162:165], v232 offset:36864
	ds_read_b128 v[174:177], v232 offset:37888
	ds_read_b128 v[218:221], v232 offset:38912
	ds_read_b128 v[234:237], v232 offset:39936
	global_load_lds_dwordx4 v[146:147], off
	v_lshl_add_u64 v[146:147], s[16:17], 0, v[210:211]
	s_mov_b32 m0, s84
	s_nop 0
	global_load_lds_dwordx4 v[146:147], off
	s_waitcnt lgkmcnt(8)
	s_barrier
	s_waitcnt lgkmcnt(0)
	s_waitcnt lgkmcnt(0)
	v_mfma_f32_16x16x32_bf16 v[50:53], v[70:73], v[114:117], v[50:53]
	v_mfma_f32_16x16x32_bf16 v[202:205], v[74:77], v[126:129], v[50:53]
	v_mfma_f32_16x16x32_bf16 v[50:53], v[98:101], v[114:117], v[54:57]
	v_mfma_f32_16x16x32_bf16 v[198:201], v[110:113], v[126:129], v[50:53]
	v_mfma_f32_16x16x32_bf16 v[50:53], v[70:73], v[130:133], v[58:61]
	v_mfma_f32_16x16x32_bf16 v[182:185], v[74:77], v[142:145], v[50:53]
	v_mfma_f32_16x16x32_bf16 v[50:53], v[98:101], v[130:133], v[150:153]
	v_mfma_f32_16x16x32_bf16 v[178:181], v[110:113], v[142:145], v[50:53]
	v_mfma_f32_16x16x32_bf16 v[50:53], v[70:73], v[162:165], v[158:161]
	v_mfma_f32_16x16x32_bf16 v[158:161], v[74:77], v[174:177], v[50:53]
	v_mfma_f32_16x16x32_bf16 v[50:53], v[98:101], v[162:165], v[154:157]
	v_mfma_f32_16x16x32_bf16 v[154:157], v[110:113], v[174:177], v[50:53]
	v_mfma_f32_16x16x32_bf16 v[50:53], v[70:73], v[218:221], v[138:141]
	v_mfma_f32_16x16x32_bf16 v[138:141], v[74:77], v[234:237], v[50:53]
	v_mfma_f32_16x16x32_bf16 v[50:53], v[98:101], v[218:221], v[134:137]
	v_mfma_f32_16x16x32_bf16 v[134:137], v[110:113], v[234:237], v[50:53]
	s_barrier
	s_add_i32 s16, 0, 0x1c000
	s_add_i32 s17, s65, s22
	v_add_u32_e32 v0, s16, v230
	v_lshl_add_u64 v[146:147], v[222:223], 0, s[20:21]
	s_mov_b32 m0, s17
	ds_read_b128 v[50:53], v0
	ds_read_b128 v[54:57], v0 offset:1024
	ds_read_b128 v[58:61], v0 offset:2048
	ds_read_b128 v[150:153], v0 offset:3072
	global_load_lds_dwordx4 v[146:147], off
	v_lshl_add_u64 v[146:147], v[226:227], 0, s[20:21]
	s_add_i32 m0, s17, 0x2000
	s_nop 0
	global_load_lds_dwordx4 v[146:147], off
	s_barrier
	s_waitcnt lgkmcnt(0)
	s_waitcnt lgkmcnt(0)
	v_mfma_f32_16x16x32_bf16 v[18:21], v[58:61], v[114:117], v[18:21]
	v_mfma_f32_16x16x32_bf16 v[190:193], v[150:153], v[126:129], v[18:21]
	v_mfma_f32_16x16x32_bf16 v[18:21], v[50:53], v[130:133], v[22:25]
	v_mfma_f32_16x16x32_bf16 v[170:173], v[54:57], v[142:145], v[18:21]
	v_mfma_f32_16x16x32_bf16 v[18:21], v[58:61], v[130:133], v[26:29]
	v_mfma_f32_16x16x32_bf16 v[146:149], v[50:53], v[114:117], v[186:189]
	v_mfma_f32_16x16x32_bf16 v[166:169], v[150:153], v[142:145], v[18:21]
	v_mfma_f32_16x16x32_bf16 v[18:21], v[50:53], v[162:165], v[30:33]
	v_mfma_f32_16x16x32_bf16 v[194:197], v[54:57], v[126:129], v[146:149]
	v_mfma_f32_16x16x32_bf16 v[146:149], v[54:57], v[174:177], v[18:21]
	v_mfma_f32_16x16x32_bf16 v[18:21], v[58:61], v[162:165], v[34:37]
	v_mfma_f32_16x16x32_bf16 v[142:145], v[150:153], v[174:177], v[18:21]
	v_mfma_f32_16x16x32_bf16 v[18:21], v[50:53], v[218:221], v[38:41]
	v_mfma_f32_16x16x32_bf16 v[130:133], v[54:57], v[234:237], v[18:21]
	v_mfma_f32_16x16x32_bf16 v[18:21], v[58:61], v[218:221], v[42:45]
	v_mfma_f32_16x16x32_bf16 v[126:129], v[150:153], v[234:237], v[18:21]
	s_mov_b32 m0, s91
	v_lshl_add_u64 v[114:115], v[238:239], 0, s[20:21]
	s_barrier
	s_nop 2
	ds_read_b128 v[18:21], v232 offset:49152
	ds_read_b128 v[22:25], v232 offset:50176
	ds_read_b128 v[26:29], v232 offset:51200
	ds_read_b128 v[30:33], v232 offset:52224
	ds_read_b128 v[34:37], v232 offset:53248
	ds_read_b128 v[38:41], v232 offset:54272
	ds_read_b128 v[42:45], v232 offset:55296
	ds_read_b128 v[162:165], v232 offset:56320
	global_load_lds_dwordx4 v[114:115], off
	v_lshl_add_u64 v[114:115], v[240:241], 0, s[20:21]
	s_mov_b32 m0, s59
	s_nop 0
	global_load_lds_dwordx4 v[114:115], off
	s_barrier
	s_waitcnt lgkmcnt(0)
	s_waitcnt lgkmcnt(0)
	v_mfma_f32_16x16x32_bf16 v[114:117], v[70:73], v[18:21], v[122:125]
	v_mfma_f32_16x16x32_bf16 v[106:109], v[70:73], v[26:29], v[106:109]
	v_mfma_f32_16x16x32_bf16 v[90:93], v[70:73], v[34:37], v[90:93]
	v_mfma_f32_16x16x32_bf16 v[2:5], v[70:73], v[42:45], v[2:5]
	v_mfma_f32_16x16x32_bf16 v[122:125], v[74:77], v[22:25], v[114:117]
	v_mfma_f32_16x16x32_bf16 v[114:117], v[98:101], v[18:21], v[118:121]
	v_mfma_f32_16x16x32_bf16 v[106:109], v[74:77], v[30:33], v[106:109]
	v_mfma_f32_16x16x32_bf16 v[102:105], v[98:101], v[26:29], v[102:105]
	v_mfma_f32_16x16x32_bf16 v[90:93], v[74:77], v[38:41], v[90:93]
	v_mfma_f32_16x16x32_bf16 v[86:89], v[98:101], v[34:37], v[86:89]
	v_mfma_f32_16x16x32_bf16 v[74:77], v[74:77], v[162:165], v[2:5]
	v_mfma_f32_16x16x32_bf16 v[2:5], v[98:101], v[42:45], v[6:9]
	v_mfma_f32_16x16x32_bf16 v[118:121], v[110:113], v[22:25], v[114:117]
	v_mfma_f32_16x16x32_bf16 v[102:105], v[110:113], v[30:33], v[102:105]
	v_mfma_f32_16x16x32_bf16 v[86:89], v[110:113], v[38:41], v[86:89]
	v_mfma_f32_16x16x32_bf16 v[70:73], v[110:113], v[162:165], v[2:5]
	s_barrier
	s_add_u32 s14, s14, 0x40080
	s_addc_u32 s15, s15, 0
	s_add_i32 s16, s16, s22
	v_lshl_add_u64 v[2:3], s[14:15], 0, v[208:209]
	s_mov_b32 m0, s16
	s_nop 0
	global_load_lds_dwordx4 v[2:3], off
	v_lshl_add_u64 v[2:3], s[14:15], 0, v[212:213]
	s_add_i32 m0, s16, 0x2000
	s_nop 0
	global_load_lds_dwordx4 v[2:3], off
	s_waitcnt vmcnt(6)
	s_barrier
	v_mfma_f32_16x16x32_bf16 v[2:5], v[50:53], v[18:21], v[10:13]
	v_mfma_f32_16x16x32_bf16 v[114:117], v[54:57], v[22:25], v[2:5]
	v_mfma_f32_16x16x32_bf16 v[2:5], v[58:61], v[18:21], v[14:17]
	v_mfma_f32_16x16x32_bf16 v[110:113], v[150:153], v[22:25], v[2:5]
	v_mfma_f32_16x16x32_bf16 v[2:5], v[50:53], v[26:29], v[46:49]
	v_mfma_f32_16x16x32_bf16 v[98:101], v[54:57], v[30:33], v[2:5]
	v_mfma_f32_16x16x32_bf16 v[2:5], v[58:61], v[26:29], v[94:97]
	v_mfma_f32_16x16x32_bf16 v[94:97], v[150:153], v[30:33], v[2:5]
	v_mfma_f32_16x16x32_bf16 v[2:5], v[50:53], v[34:37], v[82:85]
	v_mfma_f32_16x16x32_bf16 v[82:85], v[54:57], v[38:41], v[2:5]
	v_mfma_f32_16x16x32_bf16 v[2:5], v[58:61], v[34:37], v[78:81]
	v_mfma_f32_16x16x32_bf16 v[78:81], v[150:153], v[38:41], v[2:5]
	v_mfma_f32_16x16x32_bf16 v[2:5], v[50:53], v[42:45], v[66:69]
	v_mfma_f32_16x16x32_bf16 v[66:69], v[54:57], v[162:165], v[2:5]
	v_mfma_f32_16x16x32_bf16 v[2:5], v[58:61], v[42:45], v[62:65]
	v_mfma_f32_16x16x32_bf16 v[62:65], v[150:153], v[162:165], v[2:5]
	s_add_i32 s64, s64, 2
	s_add_u32 s12, s12, 0x100
	s_addc_u32 s13, s13, 0
	s_add_u32 s62, s62, 0x100
	s_addc_u32 s63, s63, 0
	s_cmp_gt_u32 s64, 13
	s_barrier
	s_cbranch_scc0 .LBB0_491
	s_branch .Lpeel_exit_g1
.LBB0_491:
	s_add_u32 s14, s12, 0xfffc0080
	s_addc_u32 s15, s13, -1
	s_add_i32 s65, 0, 0x10000
	v_add_u32_e32 v0, s65, v230
	ds_read_b128 v[2:5], v0
	ds_read_b128 v[6:9], v0 offset:1024
	ds_read_b128 v[10:13], v0 offset:2048
	ds_read_b128 v[14:17], v0 offset:3072
	s_cmp_eq_u32 s64, 12
	s_cselect_b32 s17, s9, s15
	s_cselect_b32 s16, s11, s14
	s_cselect_b32 s15, s39, s63
	s_cselect_b32 s14, s41, s62
	v_lshl_add_u64 v[50:51], s[12:13], 0, v[214:215]
	s_add_i32 m0, s23, 0xc000
	ds_read_b128 v[18:21], v232
	ds_read_b128 v[22:25], v232 offset:1024
	ds_read_b128 v[26:29], v232 offset:2048
	ds_read_b128 v[30:33], v232 offset:3072
	ds_read_b128 v[34:37], v232 offset:4096
	ds_read_b128 v[38:41], v232 offset:5120
	ds_read_b128 v[42:45], v232 offset:6144
	ds_read_b128 v[46:49], v232 offset:7168
	global_load_lds_dwordx4 v[50:51], off
	v_lshl_add_u64 v[50:51], s[12:13], 0, v[216:217]
	s_add_i32 m0, s23, 0xe000
	s_nop 0
	global_load_lds_dwordx4 v[50:51], off
	s_waitcnt lgkmcnt(8)
	s_barrier
	s_waitcnt lgkmcnt(0)
	s_waitcnt lgkmcnt(0)
	v_mfma_f32_16x16x32_bf16 v[158:161], v[2:5], v[34:37], v[158:161]
	v_mfma_f32_16x16x32_bf16 v[154:157], v[10:13], v[34:37], v[154:157]
	v_mfma_f32_16x16x32_bf16 v[138:141], v[2:5], v[42:45], v[138:141]
	v_mfma_f32_16x16x32_bf16 v[134:137], v[10:13], v[42:45], v[134:137]
	v_mfma_f32_16x16x32_bf16 v[50:53], v[2:5], v[18:21], v[202:205]
	v_mfma_f32_16x16x32_bf16 v[54:57], v[10:13], v[18:21], v[198:201]
	v_mfma_f32_16x16x32_bf16 v[58:61], v[2:5], v[26:29], v[182:185]
	v_mfma_f32_16x16x32_bf16 v[150:153], v[10:13], v[26:29], v[178:181]
	v_mfma_f32_16x16x32_bf16 v[158:161], v[6:9], v[38:41], v[158:161]
	v_mfma_f32_16x16x32_bf16 v[154:157], v[14:17], v[38:41], v[154:157]
	v_mfma_f32_16x16x32_bf16 v[138:141], v[6:9], v[46:49], v[138:141]
	v_mfma_f32_16x16x32_bf16 v[134:137], v[14:17], v[46:49], v[134:137]
	v_mfma_f32_16x16x32_bf16 v[50:53], v[6:9], v[22:25], v[50:53]
	v_mfma_f32_16x16x32_bf16 v[54:57], v[14:17], v[22:25], v[54:57]
	v_mfma_f32_16x16x32_bf16 v[58:61], v[6:9], v[30:33], v[58:61]
	v_mfma_f32_16x16x32_bf16 v[150:153], v[14:17], v[30:33], v[150:153]
	s_barrier
	s_add_i32 s86, 0, 0x14000
	s_add_i32 s65, s65, s22
	v_add_u32_e32 v0, s86, v230
	v_lshl_add_u64 v[222:223], s[14:15], 0, v[208:209]
	s_mov_b32 m0, s65
	ds_read_b128 v[162:165], v0
	ds_read_b128 v[174:177], v0 offset:1024
	ds_read_b128 v[178:181], v0 offset:2048
	ds_read_b128 v[182:185], v0 offset:3072
	global_load_lds_dwordx4 v[222:223], off
	v_lshl_add_u64 v[226:227], s[14:15], 0, v[212:213]
	s_add_i32 m0, s65, 0x2000
	s_nop 0
	global_load_lds_dwordx4 v[226:227], off
	s_barrier
	s_waitcnt lgkmcnt(0)
	s_waitcnt lgkmcnt(0)
	v_mfma_f32_16x16x32_bf16 v[186:189], v[162:165], v[18:21], v[194:197]
	v_mfma_f32_16x16x32_bf16 v[18:21], v[178:181], v[18:21], v[190:193]
	v_mfma_f32_16x16x32_bf16 v[186:189], v[174:177], v[22:25], v[186:189]
	v_mfma_f32_16x16x32_bf16 v[18:21], v[182:185], v[22:25], v[18:21]
	v_mfma_f32_16x16x32_bf16 v[22:25], v[162:165], v[26:29], v[170:173]
	v_mfma_f32_16x16x32_bf16 v[26:29], v[178:181], v[26:29], v[166:169]
	v_mfma_f32_16x16x32_bf16 v[22:25], v[174:177], v[30:33], v[22:25]
	v_mfma_f32_16x16x32_bf16 v[26:29], v[182:185], v[30:33], v[26:29]
	v_mfma_f32_16x16x32_bf16 v[30:33], v[162:165], v[34:37], v[146:149]
	v_mfma_f32_16x16x32_bf16 v[34:37], v[178:181], v[34:37], v[142:145]
	v_mfma_f32_16x16x32_bf16 v[30:33], v[174:177], v[38:41], v[30:33]
	v_mfma_f32_16x16x32_bf16 v[34:37], v[182:185], v[38:41], v[34:37]
	v_mfma_f32_16x16x32_bf16 v[38:41], v[162:165], v[42:45], v[130:133]
	v_mfma_f32_16x16x32_bf16 v[42:45], v[178:181], v[42:45], v[126:129]
	v_mfma_f32_16x16x32_bf16 v[38:41], v[174:177], v[46:49], v[38:41]
	v_mfma_f32_16x16x32_bf16 v[42:45], v[182:185], v[46:49], v[42:45]
	s_mov_b32 m0, s23
	v_lshl_add_u64 v[238:239], s[16:17], 0, v[206:207]
	s_barrier
	ds_read_b128 v[46:49], v232 offset:16384
	ds_read_b128 v[126:129], v232 offset:17408
	ds_read_b128 v[130:133], v232 offset:18432
	ds_read_b128 v[142:145], v232 offset:19456
	ds_read_b128 v[146:149], v232 offset:20480
	ds_read_b128 v[166:169], v232 offset:21504
	ds_read_b128 v[170:173], v232 offset:22528
	ds_read_b128 v[190:193], v232 offset:23552
	global_load_lds_dwordx4 v[238:239], off
	v_lshl_add_u64 v[240:241], s[16:17], 0, v[210:211]
	s_mov_b32 m0, s72
	s_nop 0
	global_load_lds_dwordx4 v[240:241], off
	s_barrier
	s_waitcnt lgkmcnt(0)
	s_waitcnt lgkmcnt(0)
	v_mfma_f32_16x16x32_bf16 v[122:125], v[2:5], v[46:49], v[122:125]
	v_mfma_f32_16x16x32_bf16 v[118:121], v[10:13], v[46:49], v[118:121]
	v_mfma_f32_16x16x32_bf16 v[106:109], v[2:5], v[130:133], v[106:109]
	v_mfma_f32_16x16x32_bf16 v[102:105], v[10:13], v[130:133], v[102:105]
	v_mfma_f32_16x16x32_bf16 v[90:93], v[2:5], v[146:149], v[90:93]
	v_mfma_f32_16x16x32_bf16 v[86:89], v[10:13], v[146:149], v[86:89]
	v_mfma_f32_16x16x32_bf16 v[2:5], v[2:5], v[170:173], v[74:77]
	v_mfma_f32_16x16x32_bf16 v[122:125], v[6:9], v[126:129], v[122:125]
	v_mfma_f32_16x16x32_bf16 v[118:121], v[14:17], v[126:129], v[118:121]
	v_mfma_f32_16x16x32_bf16 v[106:109], v[6:9], v[142:145], v[106:109]
	v_mfma_f32_16x16x32_bf16 v[102:105], v[14:17], v[142:145], v[102:105]
	v_mfma_f32_16x16x32_bf16 v[90:93], v[6:9], v[166:169], v[90:93]
	v_mfma_f32_16x16x32_bf16 v[86:89], v[14:17], v[166:169], v[86:89]
	v_mfma_f32_16x16x32_bf16 v[2:5], v[6:9], v[190:193], v[2:5]
	v_mfma_f32_16x16x32_bf16 v[6:9], v[10:13], v[170:173], v[70:73]
	v_mfma_f32_16x16x32_bf16 v[6:9], v[14:17], v[190:193], v[6:9]
	s_barrier
	s_add_u32 s66, s14, 0x40000
	s_addc_u32 s67, s15, 0
	s_add_i32 s65, s86, s22
	v_lshl_add_u64 v[10:11], s[66:67], 0, v[208:209]
	s_mov_b32 m0, s65
	s_nop 0
	global_load_lds_dwordx4 v[10:11], off
	v_lshl_add_u64 v[10:11], s[66:67], 0, v[212:213]
	s_add_i32 m0, s65, 0x2000
	s_nop 0
	global_load_lds_dwordx4 v[10:11], off
	s_waitcnt vmcnt(6)
	s_barrier
	v_mfma_f32_16x16x32_bf16 v[70:73], v[178:181], v[130:133], v[94:97]
	v_mfma_f32_16x16x32_bf16 v[94:97], v[182:185], v[142:145], v[70:73]
	v_mfma_f32_16x16x32_bf16 v[70:73], v[162:165], v[146:149], v[82:85]
	v_mfma_f32_16x16x32_bf16 v[82:85], v[174:177], v[166:169], v[70:73]
	v_mfma_f32_16x16x32_bf16 v[70:73], v[178:181], v[146:149], v[78:81]
	v_mfma_f32_16x16x32_bf16 v[66:69], v[162:165], v[170:173], v[66:69]
	v_mfma_f32_16x16x32_bf16 v[62:65], v[178:181], v[170:173], v[62:65]
	v_mfma_f32_16x16x32_bf16 v[10:13], v[162:165], v[46:49], v[114:117]
	v_mfma_f32_16x16x32_bf16 v[14:17], v[178:181], v[46:49], v[110:113]
	v_mfma_f32_16x16x32_bf16 v[46:49], v[162:165], v[130:133], v[98:101]
	v_mfma_f32_16x16x32_bf16 v[78:81], v[182:185], v[166:169], v[70:73]
	v_mfma_f32_16x16x32_bf16 v[66:69], v[174:177], v[190:193], v[66:69]
	v_mfma_f32_16x16x32_bf16 v[62:65], v[182:185], v[190:193], v[62:65]
	v_mfma_f32_16x16x32_bf16 v[10:13], v[174:177], v[126:129], v[10:13]
	v_mfma_f32_16x16x32_bf16 v[14:17], v[182:185], v[126:129], v[14:17]
	v_mfma_f32_16x16x32_bf16 v[46:49], v[174:177], v[142:145], v[46:49]
	s_add_i32 s65, 0, 0x18000
	v_add_u32_e32 v0, s65, v230
	s_barrier
	ds_read_b128 v[70:73], v0
	ds_read_b128 v[74:77], v0 offset:1024
	ds_read_b128 v[98:101], v0 offset:2048
	ds_read_b128 v[110:113], v0 offset:3072
	s_add_u32 s16, s16, 0x40000
	s_addc_u32 s17, s17, 0
	s_mov_b32 m0, s83
	v_lshl_add_u64 v[146:147], s[16:17], 0, v[206:207]
	ds_read_b128 v[114:117], v232 offset:32768
	ds_read_b128 v[126:129], v232 offset:33792
	ds_read_b128 v[130:133], v232 offset:34816
	ds_read_b128 v[142:145], v232 offset:35840
	ds_read_b128 v[162:165], v232 offset:36864
	ds_read_b128 v[174:177], v232 offset:37888
	ds_read_b128 v[218:221], v232 offset:38912
	ds_read_b128 v[234:237], v232 offset:39936
	global_load_lds_dwordx4 v[146:147], off
	v_lshl_add_u64 v[146:147], s[16:17], 0, v[210:211]
	s_mov_b32 m0, s84
	s_nop 0
	global_load_lds_dwordx4 v[146:147], off
	s_waitcnt lgkmcnt(8)
	s_barrier
	s_waitcnt lgkmcnt(0)
	s_waitcnt lgkmcnt(0)
	v_mfma_f32_16x16x32_bf16 v[50:53], v[70:73], v[114:117], v[50:53]
	v_mfma_f32_16x16x32_bf16 v[202:205], v[74:77], v[126:129], v[50:53]
	v_mfma_f32_16x16x32_bf16 v[50:53], v[98:101], v[114:117], v[54:57]
	v_mfma_f32_16x16x32_bf16 v[198:201], v[110:113], v[126:129], v[50:53]
	v_mfma_f32_16x16x32_bf16 v[50:53], v[70:73], v[130:133], v[58:61]
	v_mfma_f32_16x16x32_bf16 v[182:185], v[74:77], v[142:145], v[50:53]
	v_mfma_f32_16x16x32_bf16 v[50:53], v[98:101], v[130:133], v[150:153]
	v_mfma_f32_16x16x32_bf16 v[178:181], v[110:113], v[142:145], v[50:53]
	v_mfma_f32_16x16x32_bf16 v[50:53], v[70:73], v[162:165], v[158:161]
	v_mfma_f32_16x16x32_bf16 v[158:161], v[74:77], v[174:177], v[50:53]
	v_mfma_f32_16x16x32_bf16 v[50:53], v[98:101], v[162:165], v[154:157]
	v_mfma_f32_16x16x32_bf16 v[154:157], v[110:113], v[174:177], v[50:53]
	v_mfma_f32_16x16x32_bf16 v[50:53], v[70:73], v[218:221], v[138:141]
	v_mfma_f32_16x16x32_bf16 v[138:141], v[74:77], v[234:237], v[50:53]
	v_mfma_f32_16x16x32_bf16 v[50:53], v[98:101], v[218:221], v[134:137]
	v_mfma_f32_16x16x32_bf16 v[134:137], v[110:113], v[234:237], v[50:53]
	s_barrier
	s_add_i32 s16, 0, 0x1c000
	s_add_i32 s17, s65, s22
	v_add_u32_e32 v0, s16, v230
	v_lshl_add_u64 v[146:147], v[222:223], 0, s[20:21]
	s_mov_b32 m0, s17
	ds_read_b128 v[50:53], v0
	ds_read_b128 v[54:57], v0 offset:1024
	ds_read_b128 v[58:61], v0 offset:2048
	ds_read_b128 v[150:153], v0 offset:3072
	global_load_lds_dwordx4 v[146:147], off
	v_lshl_add_u64 v[146:147], v[226:227], 0, s[20:21]
	s_add_i32 m0, s17, 0x2000
	s_nop 0
	global_load_lds_dwordx4 v[146:147], off
	s_barrier
	s_waitcnt lgkmcnt(0)
	s_waitcnt lgkmcnt(0)
	v_mfma_f32_16x16x32_bf16 v[18:21], v[58:61], v[114:117], v[18:21]
	v_mfma_f32_16x16x32_bf16 v[190:193], v[150:153], v[126:129], v[18:21]
	v_mfma_f32_16x16x32_bf16 v[18:21], v[50:53], v[130:133], v[22:25]
	v_mfma_f32_16x16x32_bf16 v[170:173], v[54:57], v[142:145], v[18:21]
	v_mfma_f32_16x16x32_bf16 v[18:21], v[58:61], v[130:133], v[26:29]
	v_mfma_f32_16x16x32_bf16 v[146:149], v[50:53], v[114:117], v[186:189]
	v_mfma_f32_16x16x32_bf16 v[166:169], v[150:153], v[142:145], v[18:21]
	v_mfma_f32_16x16x32_bf16 v[18:21], v[50:53], v[162:165], v[30:33]
	v_mfma_f32_16x16x32_bf16 v[194:197], v[54:57], v[126:129], v[146:149]
	v_mfma_f32_16x16x32_bf16 v[146:149], v[54:57], v[174:177], v[18:21]
	v_mfma_f32_16x16x32_bf16 v[18:21], v[58:61], v[162:165], v[34:37]
	v_mfma_f32_16x16x32_bf16 v[142:145], v[150:153], v[174:177], v[18:21]
	v_mfma_f32_16x16x32_bf16 v[18:21], v[50:53], v[218:221], v[38:41]
	v_mfma_f32_16x16x32_bf16 v[130:133], v[54:57], v[234:237], v[18:21]
	v_mfma_f32_16x16x32_bf16 v[18:21], v[58:61], v[218:221], v[42:45]
	v_mfma_f32_16x16x32_bf16 v[126:129], v[150:153], v[234:237], v[18:21]
	s_mov_b32 m0, s91
	v_lshl_add_u64 v[114:115], v[238:239], 0, s[20:21]
	s_barrier
	s_nop 2
	ds_read_b128 v[18:21], v232 offset:49152
	ds_read_b128 v[22:25], v232 offset:50176
	ds_read_b128 v[26:29], v232 offset:51200
	ds_read_b128 v[30:33], v232 offset:52224
	ds_read_b128 v[34:37], v232 offset:53248
	ds_read_b128 v[38:41], v232 offset:54272
	ds_read_b128 v[42:45], v232 offset:55296
	ds_read_b128 v[162:165], v232 offset:56320
	global_load_lds_dwordx4 v[114:115], off
	v_lshl_add_u64 v[114:115], v[240:241], 0, s[20:21]
	s_mov_b32 m0, s59
	s_nop 0
	global_load_lds_dwordx4 v[114:115], off
	s_barrier
	s_waitcnt lgkmcnt(0)
	s_waitcnt lgkmcnt(0)
	v_mfma_f32_16x16x32_bf16 v[114:117], v[70:73], v[18:21], v[122:125]
	v_mfma_f32_16x16x32_bf16 v[106:109], v[70:73], v[26:29], v[106:109]
	v_mfma_f32_16x16x32_bf16 v[90:93], v[70:73], v[34:37], v[90:93]
	v_mfma_f32_16x16x32_bf16 v[2:5], v[70:73], v[42:45], v[2:5]
	v_mfma_f32_16x16x32_bf16 v[122:125], v[74:77], v[22:25], v[114:117]
	v_mfma_f32_16x16x32_bf16 v[114:117], v[98:101], v[18:21], v[118:121]
	v_mfma_f32_16x16x32_bf16 v[106:109], v[74:77], v[30:33], v[106:109]
	v_mfma_f32_16x16x32_bf16 v[102:105], v[98:101], v[26:29], v[102:105]
	v_mfma_f32_16x16x32_bf16 v[90:93], v[74:77], v[38:41], v[90:93]
	v_mfma_f32_16x16x32_bf16 v[86:89], v[98:101], v[34:37], v[86:89]
	v_mfma_f32_16x16x32_bf16 v[74:77], v[74:77], v[162:165], v[2:5]
	v_mfma_f32_16x16x32_bf16 v[2:5], v[98:101], v[42:45], v[6:9]
	v_mfma_f32_16x16x32_bf16 v[118:121], v[110:113], v[22:25], v[114:117]
	v_mfma_f32_16x16x32_bf16 v[102:105], v[110:113], v[30:33], v[102:105]
	v_mfma_f32_16x16x32_bf16 v[86:89], v[110:113], v[38:41], v[86:89]
	v_mfma_f32_16x16x32_bf16 v[70:73], v[110:113], v[162:165], v[2:5]
	s_barrier
	s_add_u32 s14, s14, 0x40080
	s_addc_u32 s15, s15, 0
	s_add_i32 s16, s16, s22
	v_lshl_add_u64 v[2:3], s[14:15], 0, v[208:209]
	s_mov_b32 m0, s16
	s_nop 0
	global_load_lds_dwordx4 v[2:3], off
	v_lshl_add_u64 v[2:3], s[14:15], 0, v[212:213]
	s_add_i32 m0, s16, 0x2000
	s_nop 0
	global_load_lds_dwordx4 v[2:3], off
	s_waitcnt vmcnt(6)
	s_barrier
	v_mfma_f32_16x16x32_bf16 v[2:5], v[50:53], v[18:21], v[10:13]
	v_mfma_f32_16x16x32_bf16 v[114:117], v[54:57], v[22:25], v[2:5]
	v_mfma_f32_16x16x32_bf16 v[2:5], v[58:61], v[18:21], v[14:17]
	v_mfma_f32_16x16x32_bf16 v[110:113], v[150:153], v[22:25], v[2:5]
	v_mfma_f32_16x16x32_bf16 v[2:5], v[50:53], v[26:29], v[46:49]
	v_mfma_f32_16x16x32_bf16 v[98:101], v[54:57], v[30:33], v[2:5]
	v_mfma_f32_16x16x32_bf16 v[2:5], v[58:61], v[26:29], v[94:97]
	v_mfma_f32_16x16x32_bf16 v[94:97], v[150:153], v[30:33], v[2:5]
	v_mfma_f32_16x16x32_bf16 v[2:5], v[50:53], v[34:37], v[82:85]
	v_mfma_f32_16x16x32_bf16 v[82:85], v[54:57], v[38:41], v[2:5]
	v_mfma_f32_16x16x32_bf16 v[2:5], v[58:61], v[34:37], v[78:81]
	v_mfma_f32_16x16x32_bf16 v[78:81], v[150:153], v[38:41], v[2:5]
	v_mfma_f32_16x16x32_bf16 v[2:5], v[50:53], v[42:45], v[66:69]
	v_mfma_f32_16x16x32_bf16 v[66:69], v[54:57], v[162:165], v[2:5]
	v_mfma_f32_16x16x32_bf16 v[2:5], v[58:61], v[42:45], v[62:65]
	v_mfma_f32_16x16x32_bf16 v[62:65], v[150:153], v[162:165], v[2:5]
	s_add_i32 s64, s64, 2
	s_add_u32 s12, s12, 0x100
	s_addc_u32 s13, s13, 0
	s_add_u32 s62, s62, 0x100
	s_addc_u32 s63, s63, 0
	s_cmp_gt_u32 s64, 13
	s_barrier
	s_cbranch_scc0 .LBB0_491

.LBB0_860:
	s_add_u32 vcc_lo, s12, 0x100
	s_addc_u32 vcc_hi, s13, 0
	s_mov_b32 s8, 0
	s_add_i32 s63, s8, 2
	s_add_u32 s6, s10, 0x100
	s_addc_u32 s7, s11, 0
	s_add_i32 s77, 0, 0x10000
	v_add_u32_e32 v0, s77, v234
	ds_read_b128 v[2:5], v0
	ds_read_b128 v[6:9], v0 offset:1024
	ds_read_b128 v[10:13], v0 offset:2048
	ds_read_b128 v[14:17], v0 offset:3072
	s_cmp_eq_u32 s23, s8
	s_cselect_b32 s8, s38, s6
	s_cselect_b32 s9, s39, s7
	s_cselect_b32 s13, s41, vcc_hi
	s_cselect_b32 s12, s40, vcc_lo
	v_lshl_add_u64 v[50:51], s[10:11], 0, v[214:215]
	s_add_i32 m0, s56, 0xc000
	ds_read_b128 v[18:21], v237
	ds_read_b128 v[22:25], v237 offset:1024
	ds_read_b128 v[26:29], v237 offset:2048
	ds_read_b128 v[30:33], v237 offset:3072
	ds_read_b128 v[34:37], v237 offset:4096
	ds_read_b128 v[38:41], v237 offset:5120
	ds_read_b128 v[42:45], v237 offset:6144
	ds_read_b128 v[46:49], v237 offset:7168
	global_load_lds_dwordx4 v[50:51], off
	v_lshl_add_u64 v[50:51], s[10:11], 0, v[216:217]
	s_add_i32 m0, s56, 0xe000
	s_nop 0
	global_load_lds_dwordx4 v[50:51], off
	s_waitcnt lgkmcnt(8)
	s_barrier
	s_waitcnt lgkmcnt(0)
	s_waitcnt lgkmcnt(0)
	v_mfma_f32_16x16x32_bf16 v[154:157], v[2:5], v[34:37], 0
	v_mfma_f32_16x16x32_bf16 v[150:153], v[10:13], v[34:37], 0
	v_mfma_f32_16x16x32_bf16 v[138:141], v[2:5], v[42:45], 0
	v_mfma_f32_16x16x32_bf16 v[134:137], v[10:13], v[42:45], 0
	v_mfma_f32_16x16x32_bf16 v[50:53], v[2:5], v[18:21], 0
	v_mfma_f32_16x16x32_bf16 v[54:57], v[10:13], v[18:21], 0
	v_mfma_f32_16x16x32_bf16 v[58:61], v[2:5], v[26:29], 0
	v_mfma_f32_16x16x32_bf16 v[166:169], v[10:13], v[26:29], 0
	v_mfma_f32_16x16x32_bf16 v[154:157], v[6:9], v[38:41], v[154:157]
	v_mfma_f32_16x16x32_bf16 v[150:153], v[14:17], v[38:41], v[150:153]
	v_mfma_f32_16x16x32_bf16 v[138:141], v[6:9], v[46:49], v[138:141]
	v_mfma_f32_16x16x32_bf16 v[134:137], v[14:17], v[46:49], v[134:137]
	v_mfma_f32_16x16x32_bf16 v[50:53], v[6:9], v[22:25], v[50:53]
	v_mfma_f32_16x16x32_bf16 v[54:57], v[14:17], v[22:25], v[54:57]
	v_mfma_f32_16x16x32_bf16 v[58:61], v[6:9], v[30:33], v[58:61]
	v_mfma_f32_16x16x32_bf16 v[166:169], v[14:17], v[30:33], v[166:169]
	s_barrier
	s_add_i32 s80, 0, 0x14000
	s_add_i32 s10, s77, s53
	v_add_u32_e32 v0, s80, v234
	v_lshl_add_u64 v[222:223], s[12:13], 0, v[208:209]
	s_mov_b32 m0, s10
	ds_read_b128 v[170:173], v0
	ds_read_b128 v[174:177], v0 offset:1024
	ds_read_b128 v[178:181], v0 offset:2048
	ds_read_b128 v[190:193], v0 offset:3072
	global_load_lds_dwordx4 v[222:223], off
	v_lshl_add_u64 v[226:227], s[12:13], 0, v[212:213]
	s_add_i32 m0, s10, 0x2000
	s_nop 0
	global_load_lds_dwordx4 v[226:227], off
	s_barrier
	s_waitcnt lgkmcnt(0)
	s_waitcnt lgkmcnt(0)
	v_mfma_f32_16x16x32_bf16 v[186:189], v[170:173], v[18:21], 0
	v_mfma_f32_16x16x32_bf16 v[18:21], v[178:181], v[18:21], 0
	v_mfma_f32_16x16x32_bf16 v[186:189], v[174:177], v[22:25], v[186:189]
	v_mfma_f32_16x16x32_bf16 v[18:21], v[190:193], v[22:25], v[18:21]
	v_mfma_f32_16x16x32_bf16 v[22:25], v[170:173], v[26:29], 0
	v_mfma_f32_16x16x32_bf16 v[26:29], v[178:181], v[26:29], 0
	v_mfma_f32_16x16x32_bf16 v[22:25], v[174:177], v[30:33], v[22:25]
	v_mfma_f32_16x16x32_bf16 v[26:29], v[190:193], v[30:33], v[26:29]
	v_mfma_f32_16x16x32_bf16 v[30:33], v[170:173], v[34:37], 0
	v_mfma_f32_16x16x32_bf16 v[34:37], v[178:181], v[34:37], 0
	v_mfma_f32_16x16x32_bf16 v[30:33], v[174:177], v[38:41], v[30:33]
	v_mfma_f32_16x16x32_bf16 v[34:37], v[190:193], v[38:41], v[34:37]
	v_mfma_f32_16x16x32_bf16 v[38:41], v[170:173], v[42:45], 0
	v_mfma_f32_16x16x32_bf16 v[42:45], v[178:181], v[42:45], 0
	v_mfma_f32_16x16x32_bf16 v[38:41], v[174:177], v[46:49], v[38:41]
	v_mfma_f32_16x16x32_bf16 v[42:45], v[190:193], v[46:49], v[42:45]
	s_mov_b32 m0, s56
	v_lshl_add_u64 v[228:229], s[8:9], 0, v[206:207]
	s_barrier
	ds_read_b128 v[46:49], v237 offset:16384
	ds_read_b128 v[126:129], v237 offset:17408
	ds_read_b128 v[130:133], v237 offset:18432
	ds_read_b128 v[142:145], v237 offset:19456
	ds_read_b128 v[146:149], v237 offset:20480
	ds_read_b128 v[158:161], v237 offset:21504
	ds_read_b128 v[162:165], v237 offset:22528
	ds_read_b128 v[182:185], v237 offset:23552
	global_load_lds_dwordx4 v[228:229], off
	v_lshl_add_u64 v[230:231], s[8:9], 0, v[210:211]
	s_mov_b32 m0, s57
	s_nop 0
	global_load_lds_dwordx4 v[230:231], off
	s_barrier
	s_waitcnt lgkmcnt(0)
	s_waitcnt lgkmcnt(0)
	v_mfma_f32_16x16x32_bf16 v[122:125], v[2:5], v[46:49], 0
	v_mfma_f32_16x16x32_bf16 v[118:121], v[10:13], v[46:49], 0
	v_mfma_f32_16x16x32_bf16 v[110:113], v[2:5], v[130:133], 0
	v_mfma_f32_16x16x32_bf16 v[102:105], v[10:13], v[130:133], 0
	v_mfma_f32_16x16x32_bf16 v[94:97], v[2:5], v[146:149], 0
	v_mfma_f32_16x16x32_bf16 v[86:89], v[10:13], v[146:149], 0
	v_mfma_f32_16x16x32_bf16 v[2:5], v[2:5], v[162:165], 0
	v_mfma_f32_16x16x32_bf16 v[122:125], v[6:9], v[126:129], v[122:125]
	v_mfma_f32_16x16x32_bf16 v[118:121], v[14:17], v[126:129], v[118:121]
	v_mfma_f32_16x16x32_bf16 v[110:113], v[6:9], v[142:145], v[110:113]
	v_mfma_f32_16x16x32_bf16 v[102:105], v[14:17], v[142:145], v[102:105]
	v_mfma_f32_16x16x32_bf16 v[94:97], v[6:9], v[158:161], v[94:97]
	v_mfma_f32_16x16x32_bf16 v[86:89], v[14:17], v[158:161], v[86:89]
	v_mfma_f32_16x16x32_bf16 v[2:5], v[6:9], v[182:185], v[2:5]
	v_mfma_f32_16x16x32_bf16 v[6:9], v[10:13], v[162:165], 0
	v_mfma_f32_16x16x32_bf16 v[6:9], v[14:17], v[182:185], v[6:9]
	s_barrier
	s_add_u32 s10, s12, s73
	s_addc_u32 s11, s13, 0
	s_add_i32 s12, s80, s53
	v_lshl_add_u64 v[238:239], s[10:11], 0, v[208:209]
	s_mov_b32 m0, s12
	v_lshl_add_u64 v[240:241], s[10:11], 0, v[212:213]
	global_load_lds_dwordx4 v[238:239], off
	s_add_i32 m0, s12, 0x2000
	s_nop 0
	global_load_lds_dwordx4 v[240:241], off
	s_waitcnt vmcnt(6)
	s_barrier
	v_mfma_f32_16x16x32_bf16 v[70:73], v[178:181], v[130:133], 0
	v_mfma_f32_16x16x32_bf16 v[90:93], v[190:193], v[142:145], v[70:73]
	v_mfma_f32_16x16x32_bf16 v[70:73], v[170:173], v[146:149], 0
	v_mfma_f32_16x16x32_bf16 v[82:85], v[174:177], v[158:161], v[70:73]
	v_mfma_f32_16x16x32_bf16 v[70:73], v[178:181], v[146:149], 0
	v_mfma_f32_16x16x32_bf16 v[66:69], v[170:173], v[162:165], 0
	v_mfma_f32_16x16x32_bf16 v[62:65], v[178:181], v[162:165], 0
	v_mfma_f32_16x16x32_bf16 v[10:13], v[170:173], v[46:49], 0
	v_mfma_f32_16x16x32_bf16 v[14:17], v[178:181], v[46:49], 0
	v_mfma_f32_16x16x32_bf16 v[46:49], v[170:173], v[130:133], 0
	v_mfma_f32_16x16x32_bf16 v[74:77], v[190:193], v[158:161], v[70:73]
	v_mfma_f32_16x16x32_bf16 v[66:69], v[174:177], v[182:185], v[66:69]
	v_mfma_f32_16x16x32_bf16 v[62:65], v[190:193], v[182:185], v[62:65]
	v_mfma_f32_16x16x32_bf16 v[10:13], v[174:177], v[126:129], v[10:13]
	v_mfma_f32_16x16x32_bf16 v[14:17], v[190:193], v[126:129], v[14:17]
	v_mfma_f32_16x16x32_bf16 v[46:49], v[174:177], v[142:145], v[46:49]
	s_add_i32 s10, 0, 0x18000
	v_add_u32_e32 v0, s10, v234
	s_barrier
	ds_read_b128 v[70:73], v0
	ds_read_b128 v[78:81], v0 offset:1024
	ds_read_b128 v[98:101], v0 offset:2048
	ds_read_b128 v[106:109], v0 offset:3072
	s_add_u32 s8, s8, 0xa0000
	s_addc_u32 s9, s9, 0
	s_mov_b32 m0, s58
	v_lshl_add_u64 v[146:147], s[8:9], 0, v[206:207]
	ds_read_b128 v[114:117], v237 offset:32768
	ds_read_b128 v[126:129], v237 offset:33792
	ds_read_b128 v[130:133], v237 offset:34816
	ds_read_b128 v[142:145], v237 offset:35840
	ds_read_b128 v[174:177], v237 offset:36864
	ds_read_b128 v[190:193], v237 offset:37888
	ds_read_b128 v[194:197], v237 offset:38912
	ds_read_b128 v[218:221], v237 offset:39936
	global_load_lds_dwordx4 v[146:147], off
	v_lshl_add_u64 v[146:147], s[8:9], 0, v[210:211]
	s_mov_b32 m0, s59
	s_nop 0
	global_load_lds_dwordx4 v[146:147], off
	s_waitcnt lgkmcnt(8)
	s_barrier
	s_waitcnt lgkmcnt(0)
	s_waitcnt lgkmcnt(0)
	v_mfma_f32_16x16x32_bf16 v[50:53], v[70:73], v[114:117], v[50:53]
	v_mfma_f32_16x16x32_bf16 v[202:205], v[78:81], v[126:129], v[50:53]
	v_mfma_f32_16x16x32_bf16 v[50:53], v[98:101], v[114:117], v[54:57]
	v_mfma_f32_16x16x32_bf16 v[198:201], v[106:109], v[126:129], v[50:53]
	v_mfma_f32_16x16x32_bf16 v[50:53], v[70:73], v[130:133], v[58:61]
	v_mfma_f32_16x16x32_bf16 v[178:181], v[78:81], v[142:145], v[50:53]
	v_mfma_f32_16x16x32_bf16 v[50:53], v[98:101], v[130:133], v[166:169]
	v_mfma_f32_16x16x32_bf16 v[170:173], v[106:109], v[142:145], v[50:53]
	v_mfma_f32_16x16x32_bf16 v[50:53], v[70:73], v[174:177], v[154:157]
	v_mfma_f32_16x16x32_bf16 v[154:157], v[78:81], v[190:193], v[50:53]
	v_mfma_f32_16x16x32_bf16 v[50:53], v[98:101], v[174:177], v[150:153]
	v_mfma_f32_16x16x32_bf16 v[150:153], v[106:109], v[190:193], v[50:53]
	v_mfma_f32_16x16x32_bf16 v[50:53], v[70:73], v[194:197], v[138:141]
	v_mfma_f32_16x16x32_bf16 v[138:141], v[78:81], v[218:221], v[50:53]
	v_mfma_f32_16x16x32_bf16 v[50:53], v[98:101], v[194:197], v[134:137]
	v_mfma_f32_16x16x32_bf16 v[134:137], v[106:109], v[218:221], v[50:53]
	s_barrier
	s_add_i32 s8, 0, 0x1c000
	s_add_i32 s9, s10, s53
	v_add_u32_e32 v0, s8, v234
	v_lshl_add_u64 v[146:147], v[222:223], 0, s[20:21]
	s_mov_b32 m0, s9
	ds_read_b128 v[50:53], v0
	ds_read_b128 v[54:57], v0 offset:1024
	ds_read_b128 v[58:61], v0 offset:2048
	ds_read_b128 v[166:169], v0 offset:3072
	global_load_lds_dwordx4 v[146:147], off
	v_lshl_add_u64 v[146:147], v[226:227], 0, s[20:21]
	s_add_i32 m0, s9, 0x2000
	s_nop 0
	global_load_lds_dwordx4 v[146:147], off
	s_barrier
	s_waitcnt lgkmcnt(0)
	s_waitcnt lgkmcnt(0)
	v_mfma_f32_16x16x32_bf16 v[18:21], v[58:61], v[114:117], v[18:21]
	v_mfma_f32_16x16x32_bf16 v[182:185], v[166:169], v[126:129], v[18:21]
	v_mfma_f32_16x16x32_bf16 v[18:21], v[50:53], v[130:133], v[22:25]
	v_mfma_f32_16x16x32_bf16 v[162:165], v[54:57], v[142:145], v[18:21]
	v_mfma_f32_16x16x32_bf16 v[18:21], v[58:61], v[130:133], v[26:29]
	v_mfma_f32_16x16x32_bf16 v[146:149], v[50:53], v[114:117], v[186:189]
	v_mfma_f32_16x16x32_bf16 v[158:161], v[166:169], v[142:145], v[18:21]
	v_mfma_f32_16x16x32_bf16 v[18:21], v[50:53], v[174:177], v[30:33]
	v_mfma_f32_16x16x32_bf16 v[186:189], v[54:57], v[126:129], v[146:149]
	v_mfma_f32_16x16x32_bf16 v[146:149], v[54:57], v[190:193], v[18:21]
	v_mfma_f32_16x16x32_bf16 v[18:21], v[58:61], v[174:177], v[34:37]
	v_mfma_f32_16x16x32_bf16 v[142:145], v[166:169], v[190:193], v[18:21]
	v_mfma_f32_16x16x32_bf16 v[18:21], v[50:53], v[194:197], v[38:41]
	v_mfma_f32_16x16x32_bf16 v[130:133], v[54:57], v[218:221], v[18:21]
	v_mfma_f32_16x16x32_bf16 v[18:21], v[58:61], v[194:197], v[42:45]
	v_mfma_f32_16x16x32_bf16 v[126:129], v[166:169], v[218:221], v[18:21]
	s_mov_b32 m0, s72
	v_lshl_add_u64 v[114:115], v[228:229], 0, s[20:21]
	s_barrier
	s_nop 2
	ds_read_b128 v[18:21], v237 offset:49152
	ds_read_b128 v[22:25], v237 offset:50176
	ds_read_b128 v[26:29], v237 offset:51200
	ds_read_b128 v[30:33], v237 offset:52224
	ds_read_b128 v[34:37], v237 offset:53248
	ds_read_b128 v[38:41], v237 offset:54272
	ds_read_b128 v[42:45], v237 offset:55296
	ds_read_b128 v[174:177], v237 offset:56320
	global_load_lds_dwordx4 v[114:115], off
	v_lshl_add_u64 v[114:115], v[230:231], 0, s[20:21]
	s_mov_b32 m0, s22
	s_nop 0
	global_load_lds_dwordx4 v[114:115], off
	s_barrier
	s_waitcnt lgkmcnt(0)
	s_waitcnt lgkmcnt(0)
	v_mfma_f32_16x16x32_bf16 v[114:117], v[70:73], v[18:21], v[122:125]
	v_mfma_f32_16x16x32_bf16 v[110:113], v[70:73], v[26:29], v[110:113]
	v_mfma_f32_16x16x32_bf16 v[94:97], v[70:73], v[34:37], v[94:97]
	v_mfma_f32_16x16x32_bf16 v[2:5], v[70:73], v[42:45], v[2:5]
	v_mfma_f32_16x16x32_bf16 v[122:125], v[78:81], v[22:25], v[114:117]
	v_mfma_f32_16x16x32_bf16 v[114:117], v[98:101], v[18:21], v[118:121]
	v_mfma_f32_16x16x32_bf16 v[110:113], v[78:81], v[30:33], v[110:113]
	v_mfma_f32_16x16x32_bf16 v[102:105], v[98:101], v[26:29], v[102:105]
	v_mfma_f32_16x16x32_bf16 v[94:97], v[78:81], v[38:41], v[94:97]
	v_mfma_f32_16x16x32_bf16 v[86:89], v[98:101], v[34:37], v[86:89]
	v_mfma_f32_16x16x32_bf16 v[78:81], v[78:81], v[174:177], v[2:5]
	v_mfma_f32_16x16x32_bf16 v[2:5], v[98:101], v[42:45], v[6:9]
	v_mfma_f32_16x16x32_bf16 v[118:121], v[106:109], v[22:25], v[114:117]
	v_mfma_f32_16x16x32_bf16 v[102:105], v[106:109], v[30:33], v[102:105]
	v_mfma_f32_16x16x32_bf16 v[86:89], v[106:109], v[38:41], v[86:89]
	v_mfma_f32_16x16x32_bf16 v[70:73], v[106:109], v[174:177], v[2:5]
	s_barrier
	s_add_i32 s8, s8, s53
	s_nop 0
	v_lshl_add_u64 v[2:3], v[238:239], 0, s[20:21]
	s_mov_b32 m0, s8
	s_nop 0
	global_load_lds_dwordx4 v[2:3], off
	v_lshl_add_u64 v[2:3], v[240:241], 0, s[20:21]
	s_add_i32 m0, s8, 0x2000
	s_nop 0
	global_load_lds_dwordx4 v[2:3], off
	s_waitcnt vmcnt(6)
	s_barrier
	v_mfma_f32_16x16x32_bf16 v[2:5], v[50:53], v[18:21], v[10:13]
	v_mfma_f32_16x16x32_bf16 v[114:117], v[54:57], v[22:25], v[2:5]
	v_mfma_f32_16x16x32_bf16 v[2:5], v[58:61], v[18:21], v[14:17]
	v_mfma_f32_16x16x32_bf16 v[106:109], v[166:169], v[22:25], v[2:5]
	v_mfma_f32_16x16x32_bf16 v[2:5], v[50:53], v[26:29], v[46:49]
	v_mfma_f32_16x16x32_bf16 v[98:101], v[54:57], v[30:33], v[2:5]
	v_mfma_f32_16x16x32_bf16 v[2:5], v[58:61], v[26:29], v[90:93]
	v_mfma_f32_16x16x32_bf16 v[90:93], v[166:169], v[30:33], v[2:5]
	v_mfma_f32_16x16x32_bf16 v[2:5], v[50:53], v[34:37], v[82:85]
	v_mfma_f32_16x16x32_bf16 v[82:85], v[54:57], v[38:41], v[2:5]
	v_mfma_f32_16x16x32_bf16 v[2:5], v[58:61], v[34:37], v[74:77]
	v_mfma_f32_16x16x32_bf16 v[74:77], v[166:169], v[38:41], v[2:5]
	v_mfma_f32_16x16x32_bf16 v[2:5], v[50:53], v[42:45], v[66:69]
	v_mfma_f32_16x16x32_bf16 v[66:69], v[54:57], v[174:177], v[2:5]
	v_mfma_f32_16x16x32_bf16 v[2:5], v[58:61], v[42:45], v[62:65]
	v_mfma_f32_16x16x32_bf16 v[62:65], v[166:169], v[174:177], v[2:5]
	s_add_u32 vcc_lo, vcc_lo, 0x100
	s_addc_u32 vcc_hi, vcc_hi, 0
	s_cmp_ge_u32 s63, s91
	s_mov_b64 s[10:11], s[6:7]
	s_mov_b32 s8, s63
	s_barrier
	s_cbranch_scc0 .LBB0_861
	s_branch .Lpeel_exit_g2
.LBB0_861:
	s_add_i32 s63, s8, 2
	s_add_u32 s6, s10, 0x100
	s_addc_u32 s7, s11, 0
	s_add_i32 s77, 0, 0x10000
	v_add_u32_e32 v0, s77, v234
	ds_read_b128 v[2:5], v0
	ds_read_b128 v[6:9], v0 offset:1024
	ds_read_b128 v[10:13], v0 offset:2048
	ds_read_b128 v[14:17], v0 offset:3072
	s_cmp_eq_u32 s23, s8
	s_cselect_b32 s8, s38, s6
	s_cselect_b32 s9, s39, s7
	s_cselect_b32 s13, s41, vcc_hi
	s_cselect_b32 s12, s40, vcc_lo
	v_lshl_add_u64 v[50:51], s[10:11], 0, v[214:215]
	s_add_i32 m0, s56, 0xc000
	ds_read_b128 v[18:21], v237
	ds_read_b128 v[22:25], v237 offset:1024
	ds_read_b128 v[26:29], v237 offset:2048
	ds_read_b128 v[30:33], v237 offset:3072
	ds_read_b128 v[34:37], v237 offset:4096
	ds_read_b128 v[38:41], v237 offset:5120
	ds_read_b128 v[42:45], v237 offset:6144
	ds_read_b128 v[46:49], v237 offset:7168
	global_load_lds_dwordx4 v[50:51], off
	v_lshl_add_u64 v[50:51], s[10:11], 0, v[216:217]
	s_add_i32 m0, s56, 0xe000
	s_nop 0
	global_load_lds_dwordx4 v[50:51], off
	s_waitcnt lgkmcnt(8)
	s_barrier
	s_waitcnt lgkmcnt(0)
	s_waitcnt lgkmcnt(0)
	v_mfma_f32_16x16x32_bf16 v[154:157], v[2:5], v[34:37], v[154:157]
	v_mfma_f32_16x16x32_bf16 v[150:153], v[10:13], v[34:37], v[150:153]
	v_mfma_f32_16x16x32_bf16 v[138:141], v[2:5], v[42:45], v[138:141]
	v_mfma_f32_16x16x32_bf16 v[134:137], v[10:13], v[42:45], v[134:137]
	v_mfma_f32_16x16x32_bf16 v[50:53], v[2:5], v[18:21], v[202:205]
	v_mfma_f32_16x16x32_bf16 v[54:57], v[10:13], v[18:21], v[198:201]
	v_mfma_f32_16x16x32_bf16 v[58:61], v[2:5], v[26:29], v[178:181]
	v_mfma_f32_16x16x32_bf16 v[166:169], v[10:13], v[26:29], v[170:173]
	v_mfma_f32_16x16x32_bf16 v[154:157], v[6:9], v[38:41], v[154:157]
	v_mfma_f32_16x16x32_bf16 v[150:153], v[14:17], v[38:41], v[150:153]
	v_mfma_f32_16x16x32_bf16 v[138:141], v[6:9], v[46:49], v[138:141]
	v_mfma_f32_16x16x32_bf16 v[134:137], v[14:17], v[46:49], v[134:137]
	v_mfma_f32_16x16x32_bf16 v[50:53], v[6:9], v[22:25], v[50:53]
	v_mfma_f32_16x16x32_bf16 v[54:57], v[14:17], v[22:25], v[54:57]
	v_mfma_f32_16x16x32_bf16 v[58:61], v[6:9], v[30:33], v[58:61]
	v_mfma_f32_16x16x32_bf16 v[166:169], v[14:17], v[30:33], v[166:169]
	s_barrier
	s_add_i32 s80, 0, 0x14000
	s_add_i32 s10, s77, s53
	v_add_u32_e32 v0, s80, v234
	v_lshl_add_u64 v[222:223], s[12:13], 0, v[208:209]
	s_mov_b32 m0, s10
	ds_read_b128 v[170:173], v0
	ds_read_b128 v[174:177], v0 offset:1024
	ds_read_b128 v[178:181], v0 offset:2048
	ds_read_b128 v[190:193], v0 offset:3072
	global_load_lds_dwordx4 v[222:223], off
	v_lshl_add_u64 v[226:227], s[12:13], 0, v[212:213]
	s_add_i32 m0, s10, 0x2000
	s_nop 0
	global_load_lds_dwordx4 v[226:227], off
	s_barrier
	s_waitcnt lgkmcnt(0)
	s_waitcnt lgkmcnt(0)
	v_mfma_f32_16x16x32_bf16 v[186:189], v[170:173], v[18:21], v[186:189]
	v_mfma_f32_16x16x32_bf16 v[18:21], v[178:181], v[18:21], v[182:185]
	v_mfma_f32_16x16x32_bf16 v[186:189], v[174:177], v[22:25], v[186:189]
	v_mfma_f32_16x16x32_bf16 v[18:21], v[190:193], v[22:25], v[18:21]
	v_mfma_f32_16x16x32_bf16 v[22:25], v[170:173], v[26:29], v[162:165]
	v_mfma_f32_16x16x32_bf16 v[26:29], v[178:181], v[26:29], v[158:161]
	v_mfma_f32_16x16x32_bf16 v[22:25], v[174:177], v[30:33], v[22:25]
	v_mfma_f32_16x16x32_bf16 v[26:29], v[190:193], v[30:33], v[26:29]
	v_mfma_f32_16x16x32_bf16 v[30:33], v[170:173], v[34:37], v[146:149]
	v_mfma_f32_16x16x32_bf16 v[34:37], v[178:181], v[34:37], v[142:145]
	v_mfma_f32_16x16x32_bf16 v[30:33], v[174:177], v[38:41], v[30:33]
	v_mfma_f32_16x16x32_bf16 v[34:37], v[190:193], v[38:41], v[34:37]
	v_mfma_f32_16x16x32_bf16 v[38:41], v[170:173], v[42:45], v[130:133]
	v_mfma_f32_16x16x32_bf16 v[42:45], v[178:181], v[42:45], v[126:129]
	v_mfma_f32_16x16x32_bf16 v[38:41], v[174:177], v[46:49], v[38:41]
	v_mfma_f32_16x16x32_bf16 v[42:45], v[190:193], v[46:49], v[42:45]
	s_mov_b32 m0, s56
	v_lshl_add_u64 v[228:229], s[8:9], 0, v[206:207]
	s_barrier
	ds_read_b128 v[46:49], v237 offset:16384
	ds_read_b128 v[126:129], v237 offset:17408
	ds_read_b128 v[130:133], v237 offset:18432
	ds_read_b128 v[142:145], v237 offset:19456
	ds_read_b128 v[146:149], v237 offset:20480
	ds_read_b128 v[158:161], v237 offset:21504
	ds_read_b128 v[162:165], v237 offset:22528
	ds_read_b128 v[182:185], v237 offset:23552
	global_load_lds_dwordx4 v[228:229], off
	v_lshl_add_u64 v[230:231], s[8:9], 0, v[210:211]
	s_mov_b32 m0, s57
	s_nop 0
	global_load_lds_dwordx4 v[230:231], off
	s_barrier
	s_waitcnt lgkmcnt(0)
	s_waitcnt lgkmcnt(0)
	v_mfma_f32_16x16x32_bf16 v[122:125], v[2:5], v[46:49], v[122:125]
	v_mfma_f32_16x16x32_bf16 v[118:121], v[10:13], v[46:49], v[118:121]
	v_mfma_f32_16x16x32_bf16 v[110:113], v[2:5], v[130:133], v[110:113]
	v_mfma_f32_16x16x32_bf16 v[102:105], v[10:13], v[130:133], v[102:105]
	v_mfma_f32_16x16x32_bf16 v[94:97], v[2:5], v[146:149], v[94:97]
	v_mfma_f32_16x16x32_bf16 v[86:89], v[10:13], v[146:149], v[86:89]
	v_mfma_f32_16x16x32_bf16 v[2:5], v[2:5], v[162:165], v[78:81]
	v_mfma_f32_16x16x32_bf16 v[122:125], v[6:9], v[126:129], v[122:125]
	v_mfma_f32_16x16x32_bf16 v[118:121], v[14:17], v[126:129], v[118:121]
	v_mfma_f32_16x16x32_bf16 v[110:113], v[6:9], v[142:145], v[110:113]
	v_mfma_f32_16x16x32_bf16 v[102:105], v[14:17], v[142:145], v[102:105]
	v_mfma_f32_16x16x32_bf16 v[94:97], v[6:9], v[158:161], v[94:97]
	v_mfma_f32_16x16x32_bf16 v[86:89], v[14:17], v[158:161], v[86:89]
	v_mfma_f32_16x16x32_bf16 v[2:5], v[6:9], v[182:185], v[2:5]
	v_mfma_f32_16x16x32_bf16 v[6:9], v[10:13], v[162:165], v[70:73]
	v_mfma_f32_16x16x32_bf16 v[6:9], v[14:17], v[182:185], v[6:9]
	s_barrier
	s_add_u32 s10, s12, s73
	s_addc_u32 s11, s13, 0
	s_add_i32 s12, s80, s53
	v_lshl_add_u64 v[238:239], s[10:11], 0, v[208:209]
	s_mov_b32 m0, s12
	v_lshl_add_u64 v[240:241], s[10:11], 0, v[212:213]
	global_load_lds_dwordx4 v[238:239], off
	s_add_i32 m0, s12, 0x2000
	s_nop 0
	global_load_lds_dwordx4 v[240:241], off
	s_waitcnt vmcnt(6)
	s_barrier
	v_mfma_f32_16x16x32_bf16 v[70:73], v[178:181], v[130:133], v[90:93]
	v_mfma_f32_16x16x32_bf16 v[90:93], v[190:193], v[142:145], v[70:73]
	v_mfma_f32_16x16x32_bf16 v[70:73], v[170:173], v[146:149], v[82:85]
	v_mfma_f32_16x16x32_bf16 v[82:85], v[174:177], v[158:161], v[70:73]
	v_mfma_f32_16x16x32_bf16 v[70:73], v[178:181], v[146:149], v[74:77]
	v_mfma_f32_16x16x32_bf16 v[66:69], v[170:173], v[162:165], v[66:69]
	v_mfma_f32_16x16x32_bf16 v[62:65], v[178:181], v[162:165], v[62:65]
	v_mfma_f32_16x16x32_bf16 v[10:13], v[170:173], v[46:49], v[114:117]
	v_mfma_f32_16x16x32_bf16 v[14:17], v[178:181], v[46:49], v[106:109]
	v_mfma_f32_16x16x32_bf16 v[46:49], v[170:173], v[130:133], v[98:101]
	v_mfma_f32_16x16x32_bf16 v[74:77], v[190:193], v[158:161], v[70:73]
	v_mfma_f32_16x16x32_bf16 v[66:69], v[174:177], v[182:185], v[66:69]
	v_mfma_f32_16x16x32_bf16 v[62:65], v[190:193], v[182:185], v[62:65]
	v_mfma_f32_16x16x32_bf16 v[10:13], v[174:177], v[126:129], v[10:13]
	v_mfma_f32_16x16x32_bf16 v[14:17], v[190:193], v[126:129], v[14:17]
	v_mfma_f32_16x16x32_bf16 v[46:49], v[174:177], v[142:145], v[46:49]
	s_add_i32 s10, 0, 0x18000
	v_add_u32_e32 v0, s10, v234
	s_barrier
	ds_read_b128 v[70:73], v0
	ds_read_b128 v[78:81], v0 offset:1024
	ds_read_b128 v[98:101], v0 offset:2048
	ds_read_b128 v[106:109], v0 offset:3072
	s_add_u32 s8, s8, 0xa0000
	s_addc_u32 s9, s9, 0
	s_mov_b32 m0, s58
	v_lshl_add_u64 v[146:147], s[8:9], 0, v[206:207]
	ds_read_b128 v[114:117], v237 offset:32768
	ds_read_b128 v[126:129], v237 offset:33792
	ds_read_b128 v[130:133], v237 offset:34816
	ds_read_b128 v[142:145], v237 offset:35840
	ds_read_b128 v[174:177], v237 offset:36864
	ds_read_b128 v[190:193], v237 offset:37888
	ds_read_b128 v[194:197], v237 offset:38912
	ds_read_b128 v[218:221], v237 offset:39936
	global_load_lds_dwordx4 v[146:147], off
	v_lshl_add_u64 v[146:147], s[8:9], 0, v[210:211]
	s_mov_b32 m0, s59
	s_nop 0
	global_load_lds_dwordx4 v[146:147], off
	s_waitcnt lgkmcnt(8)
	s_barrier
	s_waitcnt lgkmcnt(0)
	s_waitcnt lgkmcnt(0)
	v_mfma_f32_16x16x32_bf16 v[50:53], v[70:73], v[114:117], v[50:53]
	v_mfma_f32_16x16x32_bf16 v[202:205], v[78:81], v[126:129], v[50:53]
	v_mfma_f32_16x16x32_bf16 v[50:53], v[98:101], v[114:117], v[54:57]
	v_mfma_f32_16x16x32_bf16 v[198:201], v[106:109], v[126:129], v[50:53]
	v_mfma_f32_16x16x32_bf16 v[50:53], v[70:73], v[130:133], v[58:61]
	v_mfma_f32_16x16x32_bf16 v[178:181], v[78:81], v[142:145], v[50:53]
	v_mfma_f32_16x16x32_bf16 v[50:53], v[98:101], v[130:133], v[166:169]
	v_mfma_f32_16x16x32_bf16 v[170:173], v[106:109], v[142:145], v[50:53]
	v_mfma_f32_16x16x32_bf16 v[50:53], v[70:73], v[174:177], v[154:157]
	v_mfma_f32_16x16x32_bf16 v[154:157], v[78:81], v[190:193], v[50:53]
	v_mfma_f32_16x16x32_bf16 v[50:53], v[98:101], v[174:177], v[150:153]
	v_mfma_f32_16x16x32_bf16 v[150:153], v[106:109], v[190:193], v[50:53]
	v_mfma_f32_16x16x32_bf16 v[50:53], v[70:73], v[194:197], v[138:141]
	v_mfma_f32_16x16x32_bf16 v[138:141], v[78:81], v[218:221], v[50:53]
	v_mfma_f32_16x16x32_bf16 v[50:53], v[98:101], v[194:197], v[134:137]
	v_mfma_f32_16x16x32_bf16 v[134:137], v[106:109], v[218:221], v[50:53]
	s_barrier
	s_add_i32 s8, 0, 0x1c000
	s_add_i32 s9, s10, s53
	v_add_u32_e32 v0, s8, v234
	v_lshl_add_u64 v[146:147], v[222:223], 0, s[20:21]
	s_mov_b32 m0, s9
	ds_read_b128 v[50:53], v0
	ds_read_b128 v[54:57], v0 offset:1024
	ds_read_b128 v[58:61], v0 offset:2048
	ds_read_b128 v[166:169], v0 offset:3072
	global_load_lds_dwordx4 v[146:147], off
	v_lshl_add_u64 v[146:147], v[226:227], 0, s[20:21]
	s_add_i32 m0, s9, 0x2000
	s_nop 0
	global_load_lds_dwordx4 v[146:147], off
	s_barrier
	s_waitcnt lgkmcnt(0)
	s_waitcnt lgkmcnt(0)
	v_mfma_f32_16x16x32_bf16 v[18:21], v[58:61], v[114:117], v[18:21]
	v_mfma_f32_16x16x32_bf16 v[182:185], v[166:169], v[126:129], v[18:21]
	v_mfma_f32_16x16x32_bf16 v[18:21], v[50:53], v[130:133], v[22:25]
	v_mfma_f32_16x16x32_bf16 v[162:165], v[54:57], v[142:145], v[18:21]
	v_mfma_f32_16x16x32_bf16 v[18:21], v[58:61], v[130:133], v[26:29]
	v_mfma_f32_16x16x32_bf16 v[146:149], v[50:53], v[114:117], v[186:189]
	v_mfma_f32_16x16x32_bf16 v[158:161], v[166:169], v[142:145], v[18:21]
	v_mfma_f32_16x16x32_bf16 v[18:21], v[50:53], v[174:177], v[30:33]
	v_mfma_f32_16x16x32_bf16 v[186:189], v[54:57], v[126:129], v[146:149]
	v_mfma_f32_16x16x32_bf16 v[146:149], v[54:57], v[190:193], v[18:21]
	v_mfma_f32_16x16x32_bf16 v[18:21], v[58:61], v[174:177], v[34:37]
	v_mfma_f32_16x16x32_bf16 v[142:145], v[166:169], v[190:193], v[18:21]
	v_mfma_f32_16x16x32_bf16 v[18:21], v[50:53], v[194:197], v[38:41]
	v_mfma_f32_16x16x32_bf16 v[130:133], v[54:57], v[218:221], v[18:21]
	v_mfma_f32_16x16x32_bf16 v[18:21], v[58:61], v[194:197], v[42:45]
	v_mfma_f32_16x16x32_bf16 v[126:129], v[166:169], v[218:221], v[18:21]
	s_mov_b32 m0, s72
	v_lshl_add_u64 v[114:115], v[228:229], 0, s[20:21]
	s_barrier
	s_nop 2
	ds_read_b128 v[18:21], v237 offset:49152
	ds_read_b128 v[22:25], v237 offset:50176
	ds_read_b128 v[26:29], v237 offset:51200
	ds_read_b128 v[30:33], v237 offset:52224
	ds_read_b128 v[34:37], v237 offset:53248
	ds_read_b128 v[38:41], v237 offset:54272
	ds_read_b128 v[42:45], v237 offset:55296
	ds_read_b128 v[174:177], v237 offset:56320
	global_load_lds_dwordx4 v[114:115], off
	v_lshl_add_u64 v[114:115], v[230:231], 0, s[20:21]
	s_mov_b32 m0, s22
	s_nop 0
	global_load_lds_dwordx4 v[114:115], off
	s_barrier
	s_waitcnt lgkmcnt(0)
	s_waitcnt lgkmcnt(0)
	v_mfma_f32_16x16x32_bf16 v[114:117], v[70:73], v[18:21], v[122:125]
	v_mfma_f32_16x16x32_bf16 v[110:113], v[70:73], v[26:29], v[110:113]
	v_mfma_f32_16x16x32_bf16 v[94:97], v[70:73], v[34:37], v[94:97]
	v_mfma_f32_16x16x32_bf16 v[2:5], v[70:73], v[42:45], v[2:5]
	v_mfma_f32_16x16x32_bf16 v[122:125], v[78:81], v[22:25], v[114:117]
	v_mfma_f32_16x16x32_bf16 v[114:117], v[98:101], v[18:21], v[118:121]
	v_mfma_f32_16x16x32_bf16 v[110:113], v[78:81], v[30:33], v[110:113]
	v_mfma_f32_16x16x32_bf16 v[102:105], v[98:101], v[26:29], v[102:105]
	v_mfma_f32_16x16x32_bf16 v[94:97], v[78:81], v[38:41], v[94:97]
	v_mfma_f32_16x16x32_bf16 v[86:89], v[98:101], v[34:37], v[86:89]
	v_mfma_f32_16x16x32_bf16 v[78:81], v[78:81], v[174:177], v[2:5]
	v_mfma_f32_16x16x32_bf16 v[2:5], v[98:101], v[42:45], v[6:9]
	v_mfma_f32_16x16x32_bf16 v[118:121], v[106:109], v[22:25], v[114:117]
	v_mfma_f32_16x16x32_bf16 v[102:105], v[106:109], v[30:33], v[102:105]
	v_mfma_f32_16x16x32_bf16 v[86:89], v[106:109], v[38:41], v[86:89]
	v_mfma_f32_16x16x32_bf16 v[70:73], v[106:109], v[174:177], v[2:5]
	s_barrier
	s_add_i32 s8, s8, s53
	s_nop 0
	v_lshl_add_u64 v[2:3], v[238:239], 0, s[20:21]
	s_mov_b32 m0, s8
	s_nop 0
	global_load_lds_dwordx4 v[2:3], off
	v_lshl_add_u64 v[2:3], v[240:241], 0, s[20:21]
	s_add_i32 m0, s8, 0x2000
	s_nop 0
	global_load_lds_dwordx4 v[2:3], off
	s_waitcnt vmcnt(6)
	s_barrier
	v_mfma_f32_16x16x32_bf16 v[2:5], v[50:53], v[18:21], v[10:13]
	v_mfma_f32_16x16x32_bf16 v[114:117], v[54:57], v[22:25], v[2:5]
	v_mfma_f32_16x16x32_bf16 v[2:5], v[58:61], v[18:21], v[14:17]
	v_mfma_f32_16x16x32_bf16 v[106:109], v[166:169], v[22:25], v[2:5]
	v_mfma_f32_16x16x32_bf16 v[2:5], v[50:53], v[26:29], v[46:49]
	v_mfma_f32_16x16x32_bf16 v[98:101], v[54:57], v[30:33], v[2:5]
	v_mfma_f32_16x16x32_bf16 v[2:5], v[58:61], v[26:29], v[90:93]
	v_mfma_f32_16x16x32_bf16 v[90:93], v[166:169], v[30:33], v[2:5]
	v_mfma_f32_16x16x32_bf16 v[2:5], v[50:53], v[34:37], v[82:85]
	v_mfma_f32_16x16x32_bf16 v[82:85], v[54:57], v[38:41], v[2:5]
	v_mfma_f32_16x16x32_bf16 v[2:5], v[58:61], v[34:37], v[74:77]
	v_mfma_f32_16x16x32_bf16 v[74:77], v[166:169], v[38:41], v[2:5]
	v_mfma_f32_16x16x32_bf16 v[2:5], v[50:53], v[42:45], v[66:69]
	v_mfma_f32_16x16x32_bf16 v[66:69], v[54:57], v[174:177], v[2:5]
	v_mfma_f32_16x16x32_bf16 v[2:5], v[58:61], v[42:45], v[62:65]
	v_mfma_f32_16x16x32_bf16 v[62:65], v[166:169], v[174:177], v[2:5]
	s_add_u32 vcc_lo, vcc_lo, 0x100
	s_addc_u32 vcc_hi, vcc_hi, 0
	s_cmp_ge_u32 s63, s91
	s_mov_b64 s[10:11], s[6:7]
	s_mov_b32 s8, s63
	s_barrier
	s_cbranch_scc0 .LBB0_861

.LBB0_1151:
	v_mov_b64_e32 v[2:3], 0x200
	s_ashr_i32 s13, s12, 31
	v_cmp_lt_i64_e32 vcc, s[14:15], v[2:3]
	s_lshl_b64 s[14:15], s[12:13], 19
	s_add_u32 s14, s80, s14
	s_addc_u32 s15, s83, s15
	s_and_b64 s[16:17], vcc, exec
	s_cselect_b32 s13, s15, s7
	s_cselect_b32 s54, s14, s6
	s_ashr_i32 s11, s10, 31
	s_lshl_b64 s[16:17], s[10:11], 19
	s_add_u32 s16, s23, s16
	s_addc_u32 s17, s36, s17
	s_and_b64 s[26:27], vcc, exec
	s_cselect_b32 s11, s17, s9
	s_cselect_b32 s55, s16, s8
	s_add_u32 s6, s6, 0x40080
	s_addc_u32 s7, s7, 0
	s_add_u32 s56, s8, 0x100
	s_addc_u32 s57, s9, 0
	s_mov_b32 s58, -2
	s_add_u32 s8, s6, 0xfffc0080
	s_addc_u32 s9, s7, -1
	s_add_i32 s59, 0, 0x10000
	v_add_u32_e32 v0, s59, v249
	ds_read_b128 v[2:5], v0
	ds_read_b128 v[6:9], v0 offset:1024
	ds_read_b128 v[10:13], v0 offset:2048
	ds_read_b128 v[14:17], v0 offset:3072
	s_cmp_eq_u32 s58, 12
	s_cselect_b32 s27, s13, s9
	s_cselect_b32 s26, s54, s8
	s_cselect_b32 s9, s11, s57
	s_cselect_b32 s8, s55, s56
	v_lshl_add_u64 v[50:51], s[6:7], 0, v[234:235]
	s_add_i32 m0, s38, 0xc000
	ds_read_b128 v[18:21], v222
	ds_read_b128 v[22:25], v222 offset:1024
	ds_read_b128 v[26:29], v222 offset:2048
	ds_read_b128 v[30:33], v222 offset:3072
	ds_read_b128 v[34:37], v222 offset:4096
	ds_read_b128 v[38:41], v222 offset:5120
	ds_read_b128 v[42:45], v222 offset:6144
	ds_read_b128 v[46:49], v222 offset:7168
	global_load_lds_dwordx4 v[50:51], off
	v_lshl_add_u64 v[50:51], s[6:7], 0, v[236:237]
	s_add_i32 m0, s38, 0xe000
	s_nop 0
	global_load_lds_dwordx4 v[50:51], off
	s_waitcnt lgkmcnt(8)
	s_barrier
	s_waitcnt lgkmcnt(0)
	s_waitcnt lgkmcnt(0)
	v_mfma_f32_16x16x32_bf16 v[150:153], v[10:13], v[42:45], 0
	v_mfma_f32_16x16x32_bf16 v[50:53], v[2:5], v[18:21], 0
	v_mfma_f32_16x16x32_bf16 v[54:57], v[10:13], v[18:21], 0
	v_mfma_f32_16x16x32_bf16 v[58:61], v[2:5], v[26:29], 0
	v_mfma_f32_16x16x32_bf16 v[62:65], v[10:13], v[26:29], 0
	v_mfma_f32_16x16x32_bf16 v[66:69], v[2:5], v[34:37], 0
	v_mfma_f32_16x16x32_bf16 v[70:73], v[10:13], v[34:37], 0
	v_mfma_f32_16x16x32_bf16 v[74:77], v[2:5], v[42:45], 0
	v_mfma_f32_16x16x32_bf16 v[150:153], v[14:17], v[46:49], v[150:153]
	v_mfma_f32_16x16x32_bf16 v[50:53], v[6:9], v[22:25], v[50:53]
	v_mfma_f32_16x16x32_bf16 v[54:57], v[14:17], v[22:25], v[54:57]
	v_mfma_f32_16x16x32_bf16 v[58:61], v[6:9], v[30:33], v[58:61]
	v_mfma_f32_16x16x32_bf16 v[62:65], v[14:17], v[30:33], v[62:65]
	v_mfma_f32_16x16x32_bf16 v[66:69], v[6:9], v[38:41], v[66:69]
	v_mfma_f32_16x16x32_bf16 v[70:73], v[14:17], v[38:41], v[70:73]
	v_mfma_f32_16x16x32_bf16 v[74:77], v[6:9], v[46:49], v[74:77]
	s_barrier
	s_add_i32 s64, 0, 0x14000
	s_add_i32 s59, s59, s37
	v_add_u32_e32 v0, s64, v249
	v_lshl_add_u64 v[238:239], s[8:9], 0, v[230:231]
	s_mov_b32 m0, s59
	ds_read_b128 v[154:157], v0
	ds_read_b128 v[166:169], v0 offset:1024
	ds_read_b128 v[170:173], v0 offset:2048
	ds_read_b128 v[182:185], v0 offset:3072
	global_load_lds_dwordx4 v[238:239], off
	v_lshl_add_u64 v[240:241], s[8:9], 0, v[226:227]
	s_add_i32 m0, s59, 0x2000
	s_nop 0
	global_load_lds_dwordx4 v[240:241], off
	s_barrier
	s_waitcnt lgkmcnt(0)
	s_waitcnt lgkmcnt(0)
	v_mfma_f32_16x16x32_bf16 v[186:189], v[154:157], v[18:21], 0
	v_mfma_f32_16x16x32_bf16 v[18:21], v[170:173], v[18:21], 0
	v_mfma_f32_16x16x32_bf16 v[194:197], v[166:169], v[22:25], v[186:189]
	v_mfma_f32_16x16x32_bf16 v[18:21], v[182:185], v[22:25], v[18:21]
	v_mfma_f32_16x16x32_bf16 v[22:25], v[154:157], v[26:29], 0
	v_mfma_f32_16x16x32_bf16 v[26:29], v[170:173], v[26:29], 0
	v_mfma_f32_16x16x32_bf16 v[22:25], v[166:169], v[30:33], v[22:25]
	v_mfma_f32_16x16x32_bf16 v[26:29], v[182:185], v[30:33], v[26:29]
	v_mfma_f32_16x16x32_bf16 v[30:33], v[154:157], v[34:37], 0
	v_mfma_f32_16x16x32_bf16 v[34:37], v[170:173], v[34:37], 0
	v_mfma_f32_16x16x32_bf16 v[30:33], v[166:169], v[38:41], v[30:33]
	v_mfma_f32_16x16x32_bf16 v[34:37], v[182:185], v[38:41], v[34:37]
	v_mfma_f32_16x16x32_bf16 v[38:41], v[154:157], v[42:45], 0
	v_mfma_f32_16x16x32_bf16 v[42:45], v[170:173], v[42:45], 0
	v_mfma_f32_16x16x32_bf16 v[38:41], v[166:169], v[46:49], v[38:41]
	v_mfma_f32_16x16x32_bf16 v[42:45], v[182:185], v[46:49], v[42:45]
	s_mov_b32 m0, s38
	v_lshl_add_u64 v[242:243], s[26:27], 0, v[232:233]
	s_barrier
	ds_read_b128 v[46:49], v222 offset:16384
	ds_read_b128 v[142:145], v222 offset:17408
	ds_read_b128 v[146:149], v222 offset:18432
	ds_read_b128 v[158:161], v222 offset:19456
	ds_read_b128 v[162:165], v222 offset:20480
	ds_read_b128 v[174:177], v222 offset:21504
	ds_read_b128 v[178:181], v222 offset:22528
	ds_read_b128 v[186:189], v222 offset:23552
	global_load_lds_dwordx4 v[242:243], off
	v_lshl_add_u64 v[224:225], s[26:27], 0, v[228:229]
	s_mov_b32 m0, s39
	s_nop 0
	global_load_lds_dwordx4 v[224:225], off
	s_barrier
	s_waitcnt lgkmcnt(0)
	s_waitcnt lgkmcnt(0)
	v_mfma_f32_16x16x32_bf16 v[138:141], v[2:5], v[46:49], 0
	v_mfma_f32_16x16x32_bf16 v[134:137], v[10:13], v[46:49], 0
	v_mfma_f32_16x16x32_bf16 v[122:125], v[2:5], v[146:149], 0
	v_mfma_f32_16x16x32_bf16 v[118:121], v[10:13], v[146:149], 0
	v_mfma_f32_16x16x32_bf16 v[106:109], v[2:5], v[162:165], 0
	v_mfma_f32_16x16x32_bf16 v[102:105], v[10:13], v[162:165], 0
	v_mfma_f32_16x16x32_bf16 v[2:5], v[2:5], v[178:181], 0
	v_mfma_f32_16x16x32_bf16 v[138:141], v[6:9], v[142:145], v[138:141]
	v_mfma_f32_16x16x32_bf16 v[134:137], v[14:17], v[142:145], v[134:137]
	v_mfma_f32_16x16x32_bf16 v[122:125], v[6:9], v[158:161], v[122:125]
	v_mfma_f32_16x16x32_bf16 v[118:121], v[14:17], v[158:161], v[118:121]
	v_mfma_f32_16x16x32_bf16 v[106:109], v[6:9], v[174:177], v[106:109]
	v_mfma_f32_16x16x32_bf16 v[102:105], v[14:17], v[174:177], v[102:105]
	v_mfma_f32_16x16x32_bf16 v[2:5], v[6:9], v[186:189], v[2:5]
	v_mfma_f32_16x16x32_bf16 v[6:9], v[10:13], v[178:181], 0
	v_mfma_f32_16x16x32_bf16 v[6:9], v[14:17], v[186:189], v[6:9]
	s_barrier
	s_add_u32 s62, s8, 0x40000
	s_addc_u32 s63, s9, 0
	s_add_i32 s59, s64, s37
	v_lshl_add_u64 v[10:11], s[62:63], 0, v[230:231]
	s_mov_b32 m0, s59
	s_nop 0
	global_load_lds_dwordx4 v[10:11], off
	v_lshl_add_u64 v[10:11], s[62:63], 0, v[226:227]
	s_add_i32 m0, s59, 0x2000
	s_nop 0
	global_load_lds_dwordx4 v[10:11], off
	s_waitcnt vmcnt(6)
	s_barrier
	v_mfma_f32_16x16x32_bf16 v[86:89], v[170:173], v[146:149], 0
	v_mfma_f32_16x16x32_bf16 v[110:113], v[182:185], v[158:161], v[86:89]
	v_mfma_f32_16x16x32_bf16 v[86:89], v[154:157], v[162:165], 0
	v_mfma_f32_16x16x32_bf16 v[98:101], v[166:169], v[174:177], v[86:89]
	v_mfma_f32_16x16x32_bf16 v[86:89], v[170:173], v[162:165], 0
	v_mfma_f32_16x16x32_bf16 v[82:85], v[154:157], v[178:181], 0
	v_mfma_f32_16x16x32_bf16 v[78:81], v[170:173], v[178:181], 0
	v_mfma_f32_16x16x32_bf16 v[10:13], v[154:157], v[46:49], 0
	v_mfma_f32_16x16x32_bf16 v[14:17], v[170:173], v[46:49], 0
	v_mfma_f32_16x16x32_bf16 v[46:49], v[154:157], v[146:149], 0
	v_mfma_f32_16x16x32_bf16 v[94:97], v[182:185], v[174:177], v[86:89]
	v_mfma_f32_16x16x32_bf16 v[82:85], v[166:169], v[186:189], v[82:85]
	v_mfma_f32_16x16x32_bf16 v[78:81], v[182:185], v[186:189], v[78:81]
	v_mfma_f32_16x16x32_bf16 v[10:13], v[166:169], v[142:145], v[10:13]
	v_mfma_f32_16x16x32_bf16 v[14:17], v[182:185], v[142:145], v[14:17]
	v_mfma_f32_16x16x32_bf16 v[46:49], v[166:169], v[158:161], v[46:49]
	s_add_i32 s59, 0, 0x18000
	v_add_u32_e32 v0, s59, v249
	s_barrier
	ds_read_b128 v[86:89], v0
	ds_read_b128 v[90:93], v0 offset:1024
	ds_read_b128 v[114:117], v0 offset:2048
	ds_read_b128 v[126:129], v0 offset:3072
	s_add_u32 s26, s26, 0x40000
	s_addc_u32 s27, s27, 0
	s_mov_b32 m0, s40
	v_lshl_add_u64 v[154:155], s[26:27], 0, v[232:233]
	ds_read_b128 v[130:133], v222 offset:32768
	ds_read_b128 v[142:145], v222 offset:33792
	ds_read_b128 v[146:149], v222 offset:34816
	ds_read_b128 v[158:161], v222 offset:35840
	ds_read_b128 v[206:209], v222 offset:36864
	ds_read_b128 v[210:213], v222 offset:37888
	ds_read_b128 v[214:217], v222 offset:38912
	ds_read_b128 v[218:221], v222 offset:39936
	global_load_lds_dwordx4 v[154:155], off
	v_lshl_add_u64 v[154:155], s[26:27], 0, v[228:229]
	s_mov_b32 m0, s41
	s_nop 0
	global_load_lds_dwordx4 v[154:155], off
	s_waitcnt lgkmcnt(8)
	s_barrier
	s_waitcnt lgkmcnt(0)
	s_waitcnt lgkmcnt(0)
	v_mfma_f32_16x16x32_bf16 v[50:53], v[86:89], v[130:133], v[50:53]
	v_mfma_f32_16x16x32_bf16 v[202:205], v[90:93], v[142:145], v[50:53]
	v_mfma_f32_16x16x32_bf16 v[50:53], v[114:117], v[130:133], v[54:57]
	v_mfma_f32_16x16x32_bf16 v[198:201], v[126:129], v[142:145], v[50:53]
	v_mfma_f32_16x16x32_bf16 v[50:53], v[86:89], v[146:149], v[58:61]
	v_mfma_f32_16x16x32_bf16 v[186:189], v[90:93], v[158:161], v[50:53]
	v_mfma_f32_16x16x32_bf16 v[50:53], v[114:117], v[146:149], v[62:65]
	v_mfma_f32_16x16x32_bf16 v[182:185], v[126:129], v[158:161], v[50:53]
	v_mfma_f32_16x16x32_bf16 v[50:53], v[86:89], v[206:209], v[66:69]
	v_mfma_f32_16x16x32_bf16 v[170:173], v[90:93], v[210:213], v[50:53]
	v_mfma_f32_16x16x32_bf16 v[50:53], v[114:117], v[206:209], v[70:73]
	v_mfma_f32_16x16x32_bf16 v[166:169], v[126:129], v[210:213], v[50:53]
	v_mfma_f32_16x16x32_bf16 v[50:53], v[86:89], v[214:217], v[74:77]
	v_mfma_f32_16x16x32_bf16 v[154:157], v[90:93], v[218:221], v[50:53]
	v_mfma_f32_16x16x32_bf16 v[50:53], v[114:117], v[214:217], v[150:153]
	v_mfma_f32_16x16x32_bf16 v[150:153], v[126:129], v[218:221], v[50:53]
	s_barrier
	s_add_i32 s26, 0, 0x1c000
	s_add_i32 s27, s59, s37
	v_add_u32_e32 v0, s26, v249
	v_lshl_add_u64 v[66:67], v[238:239], 0, s[20:21]
	s_mov_b32 m0, s27
	ds_read_b128 v[50:53], v0
	ds_read_b128 v[54:57], v0 offset:1024
	ds_read_b128 v[58:61], v0 offset:2048
	ds_read_b128 v[62:65], v0 offset:3072
	global_load_lds_dwordx4 v[66:67], off
	v_lshl_add_u64 v[66:67], v[240:241], 0, s[20:21]
	s_add_i32 m0, s27, 0x2000
	s_nop 0
	global_load_lds_dwordx4 v[66:67], off
	s_barrier
	s_waitcnt lgkmcnt(0)
	s_waitcnt lgkmcnt(0)
	v_mfma_f32_16x16x32_bf16 v[18:21], v[58:61], v[130:133], v[18:21]
	v_mfma_f32_16x16x32_bf16 v[190:193], v[62:65], v[142:145], v[18:21]
	v_mfma_f32_16x16x32_bf16 v[18:21], v[50:53], v[146:149], v[22:25]
	v_mfma_f32_16x16x32_bf16 v[178:181], v[54:57], v[158:161], v[18:21]
	v_mfma_f32_16x16x32_bf16 v[18:21], v[58:61], v[146:149], v[26:29]
	v_mfma_f32_16x16x32_bf16 v[174:177], v[62:65], v[158:161], v[18:21]
	v_mfma_f32_16x16x32_bf16 v[18:21], v[50:53], v[206:209], v[30:33]
	v_mfma_f32_16x16x32_bf16 v[162:165], v[54:57], v[210:213], v[18:21]
	v_mfma_f32_16x16x32_bf16 v[18:21], v[58:61], v[206:209], v[34:37]
	v_mfma_f32_16x16x32_bf16 v[158:161], v[62:65], v[210:213], v[18:21]
	v_mfma_f32_16x16x32_bf16 v[18:21], v[50:53], v[214:217], v[38:41]
	v_mfma_f32_16x16x32_bf16 v[66:69], v[50:53], v[130:133], v[194:197]
	v_mfma_f32_16x16x32_bf16 v[146:149], v[54:57], v[218:221], v[18:21]
	v_mfma_f32_16x16x32_bf16 v[18:21], v[58:61], v[214:217], v[42:45]
	v_mfma_f32_16x16x32_bf16 v[194:197], v[54:57], v[142:145], v[66:69]
	v_mfma_f32_16x16x32_bf16 v[142:145], v[62:65], v[218:221], v[18:21]
	s_mov_b32 m0, s44
	v_lshl_add_u64 v[70:71], v[242:243], 0, s[20:21]
	s_barrier
	s_nop 1
	ds_read_b128 v[18:21], v222 offset:49152
	ds_read_b128 v[22:25], v222 offset:50176
	ds_read_b128 v[26:29], v222 offset:51200
	ds_read_b128 v[30:33], v222 offset:52224
	ds_read_b128 v[34:37], v222 offset:53248
	ds_read_b128 v[38:41], v222 offset:54272
	ds_read_b128 v[42:45], v222 offset:55296
	ds_read_b128 v[66:69], v222 offset:56320
	global_load_lds_dwordx4 v[70:71], off
	v_lshl_add_u64 v[70:71], v[224:225], 0, s[20:21]
	s_mov_b32 m0, s45
	s_nop 0
	global_load_lds_dwordx4 v[70:71], off
	s_barrier
	s_waitcnt lgkmcnt(0)
	s_waitcnt lgkmcnt(0)
	v_mfma_f32_16x16x32_bf16 v[70:73], v[86:89], v[18:21], v[138:141]
	v_mfma_f32_16x16x32_bf16 v[138:141], v[90:93], v[22:25], v[70:73]
	v_mfma_f32_16x16x32_bf16 v[70:73], v[114:117], v[18:21], v[134:137]
	v_mfma_f32_16x16x32_bf16 v[134:137], v[126:129], v[22:25], v[70:73]
	v_mfma_f32_16x16x32_bf16 v[70:73], v[86:89], v[26:29], v[122:125]
	v_mfma_f32_16x16x32_bf16 v[122:125], v[90:93], v[30:33], v[70:73]
	v_mfma_f32_16x16x32_bf16 v[70:73], v[114:117], v[26:29], v[118:121]
	v_mfma_f32_16x16x32_bf16 v[118:121], v[126:129], v[30:33], v[70:73]
	v_mfma_f32_16x16x32_bf16 v[70:73], v[86:89], v[34:37], v[106:109]
	v_mfma_f32_16x16x32_bf16 v[2:5], v[86:89], v[42:45], v[2:5]
	v_mfma_f32_16x16x32_bf16 v[106:109], v[90:93], v[38:41], v[70:73]
	v_mfma_f32_16x16x32_bf16 v[70:73], v[114:117], v[34:37], v[102:105]
	v_mfma_f32_16x16x32_bf16 v[90:93], v[90:93], v[66:69], v[2:5]
	v_mfma_f32_16x16x32_bf16 v[2:5], v[114:117], v[42:45], v[6:9]
	v_mfma_f32_16x16x32_bf16 v[102:105], v[126:129], v[38:41], v[70:73]
	v_mfma_f32_16x16x32_bf16 v[86:89], v[126:129], v[66:69], v[2:5]
	s_barrier
	s_add_u32 s8, s8, 0x40080
	s_addc_u32 s9, s9, 0
	s_add_i32 s26, s26, s37
	s_nop 0
	v_lshl_add_u64 v[2:3], s[8:9], 0, v[230:231]
	s_mov_b32 m0, s26
	s_nop 0
	global_load_lds_dwordx4 v[2:3], off
	v_lshl_add_u64 v[2:3], s[8:9], 0, v[226:227]
	s_add_i32 m0, s26, 0x2000
	s_nop 0
	global_load_lds_dwordx4 v[2:3], off
	s_waitcnt vmcnt(6)
	s_barrier
	v_mfma_f32_16x16x32_bf16 v[2:5], v[50:53], v[18:21], v[10:13]
	v_mfma_f32_16x16x32_bf16 v[130:133], v[54:57], v[22:25], v[2:5]
	v_mfma_f32_16x16x32_bf16 v[2:5], v[58:61], v[18:21], v[14:17]
	v_mfma_f32_16x16x32_bf16 v[126:129], v[62:65], v[22:25], v[2:5]
	v_mfma_f32_16x16x32_bf16 v[2:5], v[50:53], v[26:29], v[46:49]
	v_mfma_f32_16x16x32_bf16 v[114:117], v[54:57], v[30:33], v[2:5]
	v_mfma_f32_16x16x32_bf16 v[2:5], v[58:61], v[26:29], v[110:113]
	v_mfma_f32_16x16x32_bf16 v[110:113], v[62:65], v[30:33], v[2:5]
	v_mfma_f32_16x16x32_bf16 v[2:5], v[50:53], v[34:37], v[98:101]
	v_mfma_f32_16x16x32_bf16 v[98:101], v[54:57], v[38:41], v[2:5]
	v_mfma_f32_16x16x32_bf16 v[2:5], v[58:61], v[34:37], v[94:97]
	v_mfma_f32_16x16x32_bf16 v[94:97], v[62:65], v[38:41], v[2:5]
	v_mfma_f32_16x16x32_bf16 v[2:5], v[50:53], v[42:45], v[82:85]
	v_mfma_f32_16x16x32_bf16 v[82:85], v[54:57], v[66:69], v[2:5]
	v_mfma_f32_16x16x32_bf16 v[2:5], v[58:61], v[42:45], v[78:81]
	v_mfma_f32_16x16x32_bf16 v[78:81], v[62:65], v[66:69], v[2:5]
	s_add_i32 s58, s58, 2
	s_add_u32 s6, s6, 0x100
	s_addc_u32 s7, s7, 0
	s_add_u32 s56, s56, 0x100
	s_addc_u32 s57, s57, 0
	s_cmp_gt_u32 s58, 13
	s_barrier
	s_cbranch_scc0 .LBB0_1152
	s_branch .Lpeel_exit_g3
.LBB0_1152:
	s_add_u32 s8, s6, 0xfffc0080
	s_addc_u32 s9, s7, -1
	s_add_i32 s59, 0, 0x10000
	v_add_u32_e32 v0, s59, v249
	ds_read_b128 v[2:5], v0
	ds_read_b128 v[6:9], v0 offset:1024
	ds_read_b128 v[10:13], v0 offset:2048
	ds_read_b128 v[14:17], v0 offset:3072
	s_cmp_eq_u32 s58, 12
	s_cselect_b32 s27, s13, s9
	s_cselect_b32 s26, s54, s8
	s_cselect_b32 s9, s11, s57
	s_cselect_b32 s8, s55, s56
	v_lshl_add_u64 v[50:51], s[6:7], 0, v[234:235]
	s_add_i32 m0, s38, 0xc000
	ds_read_b128 v[18:21], v222
	ds_read_b128 v[22:25], v222 offset:1024
	ds_read_b128 v[26:29], v222 offset:2048
	ds_read_b128 v[30:33], v222 offset:3072
	ds_read_b128 v[34:37], v222 offset:4096
	ds_read_b128 v[38:41], v222 offset:5120
	ds_read_b128 v[42:45], v222 offset:6144
	ds_read_b128 v[46:49], v222 offset:7168
	global_load_lds_dwordx4 v[50:51], off
	v_lshl_add_u64 v[50:51], s[6:7], 0, v[236:237]
	s_add_i32 m0, s38, 0xe000
	s_nop 0
	global_load_lds_dwordx4 v[50:51], off
	s_waitcnt lgkmcnt(8)
	s_barrier
	s_waitcnt lgkmcnt(0)
	s_waitcnt lgkmcnt(0)
	v_mfma_f32_16x16x32_bf16 v[150:153], v[10:13], v[42:45], v[150:153]
	v_mfma_f32_16x16x32_bf16 v[50:53], v[2:5], v[18:21], v[202:205]
	v_mfma_f32_16x16x32_bf16 v[54:57], v[10:13], v[18:21], v[198:201]
	v_mfma_f32_16x16x32_bf16 v[58:61], v[2:5], v[26:29], v[186:189]
	v_mfma_f32_16x16x32_bf16 v[62:65], v[10:13], v[26:29], v[182:185]
	v_mfma_f32_16x16x32_bf16 v[66:69], v[2:5], v[34:37], v[170:173]
	v_mfma_f32_16x16x32_bf16 v[70:73], v[10:13], v[34:37], v[166:169]
	v_mfma_f32_16x16x32_bf16 v[74:77], v[2:5], v[42:45], v[154:157]
	v_mfma_f32_16x16x32_bf16 v[150:153], v[14:17], v[46:49], v[150:153]
	v_mfma_f32_16x16x32_bf16 v[50:53], v[6:9], v[22:25], v[50:53]
	v_mfma_f32_16x16x32_bf16 v[54:57], v[14:17], v[22:25], v[54:57]
	v_mfma_f32_16x16x32_bf16 v[58:61], v[6:9], v[30:33], v[58:61]
	v_mfma_f32_16x16x32_bf16 v[62:65], v[14:17], v[30:33], v[62:65]
	v_mfma_f32_16x16x32_bf16 v[66:69], v[6:9], v[38:41], v[66:69]
	v_mfma_f32_16x16x32_bf16 v[70:73], v[14:17], v[38:41], v[70:73]
	v_mfma_f32_16x16x32_bf16 v[74:77], v[6:9], v[46:49], v[74:77]
	s_barrier
	s_add_i32 s64, 0, 0x14000
	s_add_i32 s59, s59, s37
	v_add_u32_e32 v0, s64, v249
	v_lshl_add_u64 v[238:239], s[8:9], 0, v[230:231]
	s_mov_b32 m0, s59
	ds_read_b128 v[154:157], v0
	ds_read_b128 v[166:169], v0 offset:1024
	ds_read_b128 v[170:173], v0 offset:2048
	ds_read_b128 v[182:185], v0 offset:3072
	global_load_lds_dwordx4 v[238:239], off
	v_lshl_add_u64 v[240:241], s[8:9], 0, v[226:227]
	s_add_i32 m0, s59, 0x2000
	s_nop 0
	global_load_lds_dwordx4 v[240:241], off
	s_barrier
	s_waitcnt lgkmcnt(0)
	s_waitcnt lgkmcnt(0)
	v_mfma_f32_16x16x32_bf16 v[186:189], v[154:157], v[18:21], v[194:197]
	v_mfma_f32_16x16x32_bf16 v[18:21], v[170:173], v[18:21], v[190:193]
	v_mfma_f32_16x16x32_bf16 v[194:197], v[166:169], v[22:25], v[186:189]
	v_mfma_f32_16x16x32_bf16 v[18:21], v[182:185], v[22:25], v[18:21]
	v_mfma_f32_16x16x32_bf16 v[22:25], v[154:157], v[26:29], v[178:181]
	v_mfma_f32_16x16x32_bf16 v[26:29], v[170:173], v[26:29], v[174:177]
	v_mfma_f32_16x16x32_bf16 v[22:25], v[166:169], v[30:33], v[22:25]
	v_mfma_f32_16x16x32_bf16 v[26:29], v[182:185], v[30:33], v[26:29]
	v_mfma_f32_16x16x32_bf16 v[30:33], v[154:157], v[34:37], v[162:165]
	v_mfma_f32_16x16x32_bf16 v[34:37], v[170:173], v[34:37], v[158:161]
	v_mfma_f32_16x16x32_bf16 v[30:33], v[166:169], v[38:41], v[30:33]
	v_mfma_f32_16x16x32_bf16 v[34:37], v[182:185], v[38:41], v[34:37]
	v_mfma_f32_16x16x32_bf16 v[38:41], v[154:157], v[42:45], v[146:149]
	v_mfma_f32_16x16x32_bf16 v[42:45], v[170:173], v[42:45], v[142:145]
	v_mfma_f32_16x16x32_bf16 v[38:41], v[166:169], v[46:49], v[38:41]
	v_mfma_f32_16x16x32_bf16 v[42:45], v[182:185], v[46:49], v[42:45]
	s_mov_b32 m0, s38
	v_lshl_add_u64 v[242:243], s[26:27], 0, v[232:233]
	s_barrier
	ds_read_b128 v[46:49], v222 offset:16384
	ds_read_b128 v[142:145], v222 offset:17408
	ds_read_b128 v[146:149], v222 offset:18432
	ds_read_b128 v[158:161], v222 offset:19456
	ds_read_b128 v[162:165], v222 offset:20480
	ds_read_b128 v[174:177], v222 offset:21504
	ds_read_b128 v[178:181], v222 offset:22528
	ds_read_b128 v[186:189], v222 offset:23552
	global_load_lds_dwordx4 v[242:243], off
	v_lshl_add_u64 v[224:225], s[26:27], 0, v[228:229]
	s_mov_b32 m0, s39
	s_nop 0
	global_load_lds_dwordx4 v[224:225], off
	s_barrier
	s_waitcnt lgkmcnt(0)
	s_waitcnt lgkmcnt(0)
	v_mfma_f32_16x16x32_bf16 v[138:141], v[2:5], v[46:49], v[138:141]
	v_mfma_f32_16x16x32_bf16 v[134:137], v[10:13], v[46:49], v[134:137]
	v_mfma_f32_16x16x32_bf16 v[122:125], v[2:5], v[146:149], v[122:125]
	v_mfma_f32_16x16x32_bf16 v[118:121], v[10:13], v[146:149], v[118:121]
	v_mfma_f32_16x16x32_bf16 v[106:109], v[2:5], v[162:165], v[106:109]
	v_mfma_f32_16x16x32_bf16 v[102:105], v[10:13], v[162:165], v[102:105]
	v_mfma_f32_16x16x32_bf16 v[2:5], v[2:5], v[178:181], v[90:93]
	v_mfma_f32_16x16x32_bf16 v[138:141], v[6:9], v[142:145], v[138:141]
	v_mfma_f32_16x16x32_bf16 v[134:137], v[14:17], v[142:145], v[134:137]
	v_mfma_f32_16x16x32_bf16 v[122:125], v[6:9], v[158:161], v[122:125]
	v_mfma_f32_16x16x32_bf16 v[118:121], v[14:17], v[158:161], v[118:121]
	v_mfma_f32_16x16x32_bf16 v[106:109], v[6:9], v[174:177], v[106:109]
	v_mfma_f32_16x16x32_bf16 v[102:105], v[14:17], v[174:177], v[102:105]
	v_mfma_f32_16x16x32_bf16 v[2:5], v[6:9], v[186:189], v[2:5]
	v_mfma_f32_16x16x32_bf16 v[6:9], v[10:13], v[178:181], v[86:89]
	v_mfma_f32_16x16x32_bf16 v[6:9], v[14:17], v[186:189], v[6:9]
	s_barrier
	s_add_u32 s62, s8, 0x40000
	s_addc_u32 s63, s9, 0
	s_add_i32 s59, s64, s37
	v_lshl_add_u64 v[10:11], s[62:63], 0, v[230:231]
	s_mov_b32 m0, s59
	s_nop 0
	global_load_lds_dwordx4 v[10:11], off
	v_lshl_add_u64 v[10:11], s[62:63], 0, v[226:227]
	s_add_i32 m0, s59, 0x2000
	s_nop 0
	global_load_lds_dwordx4 v[10:11], off
	s_waitcnt vmcnt(6)
	s_barrier
	v_mfma_f32_16x16x32_bf16 v[86:89], v[170:173], v[146:149], v[110:113]
	v_mfma_f32_16x16x32_bf16 v[110:113], v[182:185], v[158:161], v[86:89]
	v_mfma_f32_16x16x32_bf16 v[86:89], v[154:157], v[162:165], v[98:101]
	v_mfma_f32_16x16x32_bf16 v[98:101], v[166:169], v[174:177], v[86:89]
	v_mfma_f32_16x16x32_bf16 v[86:89], v[170:173], v[162:165], v[94:97]
	v_mfma_f32_16x16x32_bf16 v[82:85], v[154:157], v[178:181], v[82:85]
	v_mfma_f32_16x16x32_bf16 v[78:81], v[170:173], v[178:181], v[78:81]
	v_mfma_f32_16x16x32_bf16 v[10:13], v[154:157], v[46:49], v[130:133]
	v_mfma_f32_16x16x32_bf16 v[14:17], v[170:173], v[46:49], v[126:129]
	v_mfma_f32_16x16x32_bf16 v[46:49], v[154:157], v[146:149], v[114:117]
	v_mfma_f32_16x16x32_bf16 v[94:97], v[182:185], v[174:177], v[86:89]
	v_mfma_f32_16x16x32_bf16 v[82:85], v[166:169], v[186:189], v[82:85]
	v_mfma_f32_16x16x32_bf16 v[78:81], v[182:185], v[186:189], v[78:81]
	v_mfma_f32_16x16x32_bf16 v[10:13], v[166:169], v[142:145], v[10:13]
	v_mfma_f32_16x16x32_bf16 v[14:17], v[182:185], v[142:145], v[14:17]
	v_mfma_f32_16x16x32_bf16 v[46:49], v[166:169], v[158:161], v[46:49]
	s_add_i32 s59, 0, 0x18000
	v_add_u32_e32 v0, s59, v249
	s_barrier
	ds_read_b128 v[86:89], v0
	ds_read_b128 v[90:93], v0 offset:1024
	ds_read_b128 v[114:117], v0 offset:2048
	ds_read_b128 v[126:129], v0 offset:3072
	s_add_u32 s26, s26, 0x40000
	s_addc_u32 s27, s27, 0
	s_mov_b32 m0, s40
	v_lshl_add_u64 v[154:155], s[26:27], 0, v[232:233]
	ds_read_b128 v[130:133], v222 offset:32768
	ds_read_b128 v[142:145], v222 offset:33792
	ds_read_b128 v[146:149], v222 offset:34816
	ds_read_b128 v[158:161], v222 offset:35840
	ds_read_b128 v[206:209], v222 offset:36864
	ds_read_b128 v[210:213], v222 offset:37888
	ds_read_b128 v[214:217], v222 offset:38912
	ds_read_b128 v[218:221], v222 offset:39936
	global_load_lds_dwordx4 v[154:155], off
	v_lshl_add_u64 v[154:155], s[26:27], 0, v[228:229]
	s_mov_b32 m0, s41
	s_nop 0
	global_load_lds_dwordx4 v[154:155], off
	s_waitcnt lgkmcnt(8)
	s_barrier
	s_waitcnt lgkmcnt(0)
	s_waitcnt lgkmcnt(0)
	v_mfma_f32_16x16x32_bf16 v[50:53], v[86:89], v[130:133], v[50:53]
	v_mfma_f32_16x16x32_bf16 v[202:205], v[90:93], v[142:145], v[50:53]
	v_mfma_f32_16x16x32_bf16 v[50:53], v[114:117], v[130:133], v[54:57]
	v_mfma_f32_16x16x32_bf16 v[198:201], v[126:129], v[142:145], v[50:53]
	v_mfma_f32_16x16x32_bf16 v[50:53], v[86:89], v[146:149], v[58:61]
	v_mfma_f32_16x16x32_bf16 v[186:189], v[90:93], v[158:161], v[50:53]
	v_mfma_f32_16x16x32_bf16 v[50:53], v[114:117], v[146:149], v[62:65]
	v_mfma_f32_16x16x32_bf16 v[182:185], v[126:129], v[158:161], v[50:53]
	v_mfma_f32_16x16x32_bf16 v[50:53], v[86:89], v[206:209], v[66:69]
	v_mfma_f32_16x16x32_bf16 v[170:173], v[90:93], v[210:213], v[50:53]
	v_mfma_f32_16x16x32_bf16 v[50:53], v[114:117], v[206:209], v[70:73]
	v_mfma_f32_16x16x32_bf16 v[166:169], v[126:129], v[210:213], v[50:53]
	v_mfma_f32_16x16x32_bf16 v[50:53], v[86:89], v[214:217], v[74:77]
	v_mfma_f32_16x16x32_bf16 v[154:157], v[90:93], v[218:221], v[50:53]
	v_mfma_f32_16x16x32_bf16 v[50:53], v[114:117], v[214:217], v[150:153]
	v_mfma_f32_16x16x32_bf16 v[150:153], v[126:129], v[218:221], v[50:53]
	s_barrier
	s_add_i32 s26, 0, 0x1c000
	s_add_i32 s27, s59, s37
	v_add_u32_e32 v0, s26, v249
	v_lshl_add_u64 v[66:67], v[238:239], 0, s[20:21]
	s_mov_b32 m0, s27
	ds_read_b128 v[50:53], v0
	ds_read_b128 v[54:57], v0 offset:1024
	ds_read_b128 v[58:61], v0 offset:2048
	ds_read_b128 v[62:65], v0 offset:3072
	global_load_lds_dwordx4 v[66:67], off
	v_lshl_add_u64 v[66:67], v[240:241], 0, s[20:21]
	s_add_i32 m0, s27, 0x2000
	s_nop 0
	global_load_lds_dwordx4 v[66:67], off
	s_barrier
	s_waitcnt lgkmcnt(0)
	s_waitcnt lgkmcnt(0)
	v_mfma_f32_16x16x32_bf16 v[18:21], v[58:61], v[130:133], v[18:21]
	v_mfma_f32_16x16x32_bf16 v[190:193], v[62:65], v[142:145], v[18:21]
	v_mfma_f32_16x16x32_bf16 v[18:21], v[50:53], v[146:149], v[22:25]
	v_mfma_f32_16x16x32_bf16 v[178:181], v[54:57], v[158:161], v[18:21]
	v_mfma_f32_16x16x32_bf16 v[18:21], v[58:61], v[146:149], v[26:29]
	v_mfma_f32_16x16x32_bf16 v[174:177], v[62:65], v[158:161], v[18:21]
	v_mfma_f32_16x16x32_bf16 v[18:21], v[50:53], v[206:209], v[30:33]
	v_mfma_f32_16x16x32_bf16 v[162:165], v[54:57], v[210:213], v[18:21]
	v_mfma_f32_16x16x32_bf16 v[18:21], v[58:61], v[206:209], v[34:37]
	v_mfma_f32_16x16x32_bf16 v[158:161], v[62:65], v[210:213], v[18:21]
	v_mfma_f32_16x16x32_bf16 v[18:21], v[50:53], v[214:217], v[38:41]
	v_mfma_f32_16x16x32_bf16 v[66:69], v[50:53], v[130:133], v[194:197]
	v_mfma_f32_16x16x32_bf16 v[146:149], v[54:57], v[218:221], v[18:21]
	v_mfma_f32_16x16x32_bf16 v[18:21], v[58:61], v[214:217], v[42:45]
	v_mfma_f32_16x16x32_bf16 v[194:197], v[54:57], v[142:145], v[66:69]
	v_mfma_f32_16x16x32_bf16 v[142:145], v[62:65], v[218:221], v[18:21]
	s_mov_b32 m0, s44
	v_lshl_add_u64 v[70:71], v[242:243], 0, s[20:21]
	s_barrier
	s_nop 1
	ds_read_b128 v[18:21], v222 offset:49152
	ds_read_b128 v[22:25], v222 offset:50176
	ds_read_b128 v[26:29], v222 offset:51200
	ds_read_b128 v[30:33], v222 offset:52224
	ds_read_b128 v[34:37], v222 offset:53248
	ds_read_b128 v[38:41], v222 offset:54272
	ds_read_b128 v[42:45], v222 offset:55296
	ds_read_b128 v[66:69], v222 offset:56320
	global_load_lds_dwordx4 v[70:71], off
	v_lshl_add_u64 v[70:71], v[224:225], 0, s[20:21]
	s_mov_b32 m0, s45
	s_nop 0
	global_load_lds_dwordx4 v[70:71], off
	s_barrier
	s_waitcnt lgkmcnt(0)
	s_waitcnt lgkmcnt(0)
	v_mfma_f32_16x16x32_bf16 v[70:73], v[86:89], v[18:21], v[138:141]
	v_mfma_f32_16x16x32_bf16 v[138:141], v[90:93], v[22:25], v[70:73]
	v_mfma_f32_16x16x32_bf16 v[70:73], v[114:117], v[18:21], v[134:137]
	v_mfma_f32_16x16x32_bf16 v[134:137], v[126:129], v[22:25], v[70:73]
	v_mfma_f32_16x16x32_bf16 v[70:73], v[86:89], v[26:29], v[122:125]
	v_mfma_f32_16x16x32_bf16 v[122:125], v[90:93], v[30:33], v[70:73]
	v_mfma_f32_16x16x32_bf16 v[70:73], v[114:117], v[26:29], v[118:121]
	v_mfma_f32_16x16x32_bf16 v[118:121], v[126:129], v[30:33], v[70:73]
	v_mfma_f32_16x16x32_bf16 v[70:73], v[86:89], v[34:37], v[106:109]
	v_mfma_f32_16x16x32_bf16 v[2:5], v[86:89], v[42:45], v[2:5]
	v_mfma_f32_16x16x32_bf16 v[106:109], v[90:93], v[38:41], v[70:73]
	v_mfma_f32_16x16x32_bf16 v[70:73], v[114:117], v[34:37], v[102:105]
	v_mfma_f32_16x16x32_bf16 v[90:93], v[90:93], v[66:69], v[2:5]
	v_mfma_f32_16x16x32_bf16 v[2:5], v[114:117], v[42:45], v[6:9]
	v_mfma_f32_16x16x32_bf16 v[102:105], v[126:129], v[38:41], v[70:73]
	v_mfma_f32_16x16x32_bf16 v[86:89], v[126:129], v[66:69], v[2:5]
	s_barrier
	s_add_u32 s8, s8, 0x40080
	s_addc_u32 s9, s9, 0
	s_add_i32 s26, s26, s37
	s_nop 0
	v_lshl_add_u64 v[2:3], s[8:9], 0, v[230:231]
	s_mov_b32 m0, s26
	s_nop 0
	global_load_lds_dwordx4 v[2:3], off
	v_lshl_add_u64 v[2:3], s[8:9], 0, v[226:227]
	s_add_i32 m0, s26, 0x2000
	s_nop 0
	global_load_lds_dwordx4 v[2:3], off
	s_waitcnt vmcnt(6)
	s_barrier
	v_mfma_f32_16x16x32_bf16 v[2:5], v[50:53], v[18:21], v[10:13]
	v_mfma_f32_16x16x32_bf16 v[130:133], v[54:57], v[22:25], v[2:5]
	v_mfma_f32_16x16x32_bf16 v[2:5], v[58:61], v[18:21], v[14:17]
	v_mfma_f32_16x16x32_bf16 v[126:129], v[62:65], v[22:25], v[2:5]
	v_mfma_f32_16x16x32_bf16 v[2:5], v[50:53], v[26:29], v[46:49]
	v_mfma_f32_16x16x32_bf16 v[114:117], v[54:57], v[30:33], v[2:5]
	v_mfma_f32_16x16x32_bf16 v[2:5], v[58:61], v[26:29], v[110:113]
	v_mfma_f32_16x16x32_bf16 v[110:113], v[62:65], v[30:33], v[2:5]
	v_mfma_f32_16x16x32_bf16 v[2:5], v[50:53], v[34:37], v[98:101]
	v_mfma_f32_16x16x32_bf16 v[98:101], v[54:57], v[38:41], v[2:5]
	v_mfma_f32_16x16x32_bf16 v[2:5], v[58:61], v[34:37], v[94:97]
	v_mfma_f32_16x16x32_bf16 v[94:97], v[62:65], v[38:41], v[2:5]
	v_mfma_f32_16x16x32_bf16 v[2:5], v[50:53], v[42:45], v[82:85]
	v_mfma_f32_16x16x32_bf16 v[82:85], v[54:57], v[66:69], v[2:5]
	v_mfma_f32_16x16x32_bf16 v[2:5], v[58:61], v[42:45], v[78:81]
	v_mfma_f32_16x16x32_bf16 v[78:81], v[62:65], v[66:69], v[2:5]
	s_add_i32 s58, s58, 2
	s_add_u32 s6, s6, 0x100
	s_addc_u32 s7, s7, 0
	s_add_u32 s56, s56, 0x100
	s_addc_u32 s57, s57, 0
	s_cmp_gt_u32 s58, 13
	s_barrier
	s_cbranch_scc0 .LBB0_1152
